# SSD: Yoff accumulated in two independent MFMA chains (shorter dependent chain), first LDS reads interleaved C/state
# baseline (speedup 1.0000x reference)
; #define LAS __attribute__((address_space(3)))
; __device__ __forceinline__ int launder_v(int v) { asm volatile("" : "+v"(v)); return v; }
; __device__ __forceinline__ int grid_x() { int g = (int)gridDim.x; asm volatile("" : "+s"(g)); return g; }
; __device__ __forceinline__ void phase_ssd(const Params& P, int seg, unsigned char* smem) {
;     ...
;     const int tid = launder_v(threadIdx.x), lane = tid & 63, w = tid >> 6, fr = lane & 15, fq = lane >> 4;
;     const unsigned lds0 = (unsigned)(size_t)(LAS unsigned char*)smem;
;     bf16* StS = (bf16*)(smem + T_ST); float* acS = (float*)(smem + T_AC);
;     const int lt = w >> 1, pt = w & 1, tq = (lane & 15) >> 2, tp = lane & 3;
;     if (__builtin_amdgcn_readfirstlane(tid) >= 256) __builtin_amdgcn_s_setprio(1);
;     const int gx = grid_x();
.LBB0_292:
	v_readlane_b32 s14, v253, 47
	v_readlane_b32 s15, v253, 48
	s_mov_b32 s9, s82
	s_andn2_b64 vcc, exec, s[14:15]
	v_cndmask_b32_e64 v4, 0, 1, s[14:15]
	v_cmp_ne_u32_e64 s[16:17], 1, v4
	s_nop 1
	v_writelane_b32 v255, s16, 7
	s_nop 1
	v_writelane_b32 v255, s17, 8
	s_cbranch_vccnz .LBB0_338
	s_mov_b64 exec, -1
	s_mov_b64 s[0:1], s[80:81]
	s_mov_b32 s63, s82
	v_readlane_b32 s24, v254, 38
	v_readlane_b32 s52, v252, 28
	v_readlane_b32 s53, v252, 29
	v_and_b32_e32 v184, 63, v172
	v_lshrrev_b32_e32 v185, 6, v172
	v_and_b32_e32 v186, 15, v172
	v_bfe_u32 v187, v172, 4, 2
	v_bfe_u32 v188, v172, 2, 2
	v_and_b32_e32 v189, 3, v172
	v_lshrrev_b32_e32 v190, 7, v172
	v_lshrrev_b32_e32 v191, 8, v172
	v_xor_b32_e32 v190, v190, v191
	v_bfe_u32 v191, v172, 6, 1
	v_readfirstlane_b32 s73, v185
	s_nop 3
	s_lshr_b32 s55, s73, 1
	s_lshr_b32 s65, s73, 2
	s_xor_b32 s55, s55, s65
	s_bitcmp1_b32 s55, 0
	s_cbranch_scc1 .Lssd_prio1
	s_setprio 0
	s_branch .Lssd_prio_done

; #define GAS __attribute__((address_space(1)))
; __device__ __forceinline__ void phase_ssd(const Params& P, int seg, unsigned char* smem) {
;     ...
;     const int tid = launder_v(threadIdx.x), lane = tid & 63, w = tid >> 6, fr = lane & 15, fq = lane >> 4;
;     const unsigned lds0 = (unsigned)(size_t)(LAS unsigned char*)smem;
;     bf16* StS = (bf16*)(smem + T_ST); float* acS = (float*)(smem + T_AC);
;     const int lt = w >> 1, pt = w & 1, tq = (lane & 15) >> 2, tp = lane & 3;
;     if (__builtin_amdgcn_readfirstlane(tid) >= 256) __builtin_amdgcn_s_setprio(1);
;     const int gx = grid_x();
;     for (int item = blockIdx.x; item < 256; item += gx) {
;         const int xcd = item & 7, ix = item >> 3, bg = xcd * 2 + (ix >> 4), b = bg >> 3, g = bg & 7, h = g * 8 + ((ix & 15) >> 1), ph = ix & 1;
;         const float Dh = P.d_skip[h];
;         const GAS float* stg = state + (size_t)(seg & 1) * (2 * 64 * 64 * 128) + ((size_t)(b * 64 + h) * 64 + ph * 32) * 128;
;         GAS float* stw = state + (size_t)((seg + 1) & 1) * (2 * 64 * 64 * 128) + ((size_t)(b * 64 + h) * 64 + ph * 32) * 128;
;         f32x4 st[2];
; #pragma unroll
;         for (int p2 = 0; p2 < 2; ++p2)
; #pragma unroll
;             for (int j = 0; j < 4; ++j) st[p2][j] = (seg == 0) ? 0.f : stg[(size_t)(p2 * 16 + fq * 4 + j) * 128 + w * 16 + fr];
;         __syncthreads();
; #pragma unroll
;         for (int p2 = 0; p2 < 2; ++p2)
; #pragma unroll
;             for (int j = 0; j < 4; ++j) StS[(p2 * 16 + fq * 4 + j) * 136 + w * 16 + fr] = (bf16)f2bf(st[p2][j]);
;         const int nchunks = TSEG / 64 + (seg == 0 ? 1 : 0);
;         struct Pre { v4u Br[2], Cr[2]; v2u Xr, Zr; float dtl, acl, alast, aclane; }; Pre RA, RB;
;         auto chunk_row0 = [&](int ci) -> int { return (seg == 0) ? (ci == 0 ? RS : b * TSEG + (ci - 1) * 64) : b * TSEG + ci * 64; };
;         auto load_chunk = [&](int ci, Pre& R) { const int row0 = chunk_row0(ci);
; #pragma unroll
;             for (int i = 0; i < 2; ++i) { const int q = tid + 512 * i, l = q >> 4, c8 = q & 15; const GAS bf16* rp = xconv + (size_t)(row0 + l) * DXBC + g * 128 + c8 * 8;
;                 R.Br[i] = *(const GAS v4u*)(rp + 4096); R.Cr[i] = *(const GAS v4u*)(rp + 5120); }
;             { const int l = tid >> 3, p4 = (tid & 7) * 4; R.Xr = *(const GAS v2u*)(xconv + (size_t)(row0 + l) * DXBC + h * 64 + ph * 32 + p4);
.Lssd_prio_done:
	v_lshrrev_b32_e32 v170, 4, v172
	v_and_b32_e32 v171, 7, v170
	v_lshlrev_b32_e32 v171, 1, v171
	v_xor_b32_e32 v171, v171, v186
	v_lshlrev_b32_e32 v171, 4, v171
	v_lshl_add_u32 v212, v170, 8, v171
	v_lshrrev_b32_e32 v171, 3, v172
	v_and_b32_e32 v192, 7, v172
	v_mul_u32_u24_e32 v214, 80, v171
	v_lshl_add_u32 v214, v192, 3, v214
	v_mul_u32_u24_e32 v216, 72, v171
	v_lshl_add_u32 v216, v192, 3, v216
	v_lshlrev_b32_e32 v218, 2, v171
	v_add_u32_e32 v218, 0x1d800, v218
	v_and_b32_e32 v193, 7, v186
	v_lshlrev_b32_e32 v193, 1, v193
	v_lshl_add_u32 v195, v191, 4, v186
	v_lshlrev_b32_e32 v195, 8, v195
	v_add_u32_e32 v195, 0x19800, v195
	v_add_u32_e32 v170, 0, v187
	v_xor_b32_e32 v170, v170, v193
	v_lshlrev_b32_e32 v170, 4, v170
	v_lshl_add_u32 v219, v186, 8, v170
	v_add_u32_e32 v227, v195, v170
	v_add_u32_e32 v170, 4, v187
	v_xor_b32_e32 v170, v170, v193
	v_lshlrev_b32_e32 v170, 4, v170
	v_lshl_add_u32 v220, v186, 8, v170
	v_add_u32_e32 v228, v195, v170
	v_add_u32_e32 v170, 8, v187
	v_xor_b32_e32 v170, v170, v193
	v_lshlrev_b32_e32 v170, 4, v170
	v_lshl_add_u32 v221, v186, 8, v170
	v_add_u32_e32 v229, v195, v170
	v_add_u32_e32 v170, 12, v187
	v_xor_b32_e32 v170, v170, v193
	v_lshlrev_b32_e32 v170, 4, v170
	v_lshl_add_u32 v222, v186, 8, v170
	v_add_u32_e32 v230, v195, v170
	v_lshlrev_b32_e32 v231, 2, v186
	v_add_u32_e32 v231, 0x1d800, v231
	v_lshlrev_b32_e32 v232, 4, v187
	v_add_u32_e32 v232, 0x1d800, v232
	v_lshl_add_u32 v170, v187, 2, v188
	v_mul_u32_u24_e32 v233, 80, v170
	v_lshl_add_u32 v233, v191, 5, v233
	v_lshl_add_u32 v233, v189, 3, v233
	v_mul_u32_u24_e32 v235, 72, v186
	v_lshl_add_u32 v235, v191, 5, v235
	v_lshl_add_u32 v235, v187, 3, v235
	v_mul_u32_u24_e32 v237, 80, v170
	v_lshl_add_u32 v237, v189, 3, v237
	v_and_b32_e32 v171, 7, v170
	v_lshlrev_b32_e32 v171, 1, v171
	v_lshrrev_b32_e32 v192, 1, v189
	v_and_b32_e32 v195, 1, v189
	v_lshlrev_b32_e32 v195, 3, v195
	v_lshl_add_u32 v195, v170, 8, v195
	v_and_b32_e32 v194, 3, v185
	v_lshl_add_u32 v193, v194, 2, v192
	v_xor_b32_e32 v193, v193, v171
	v_lshl_add_u32 v244, v193, 4, v195
	v_lshl_add_u32 v193, v194, 2, v192
	v_add_u32_e32 v193, 2, v193
	v_xor_b32_e32 v193, v193, v171
	v_lshl_add_u32 v245, v193, 4, v195
	v_and_b32_e32 v171, 7, v186
	v_lshlrev_b32_e32 v171, 1, v171
	v_lshrrev_b32_e32 v192, 1, v187
	v_and_b32_e32 v195, 1, v187
	v_lshlrev_b32_e32 v195, 3, v195
	v_lshl_add_u32 v195, v186, 8, v195
	v_add_u32_e32 v195, 0x19800, v195
	v_lshl_add_u32 v193, v194, 2, v192
	v_xor_b32_e32 v193, v193, v171
	v_lshl_add_u32 v248, v193, 4, v195
	v_lshl_add_u32 v193, v194, 2, v192
	v_add_u32_e32 v193, 2, v193
	v_xor_b32_e32 v193, v193, v171
	v_lshl_add_u32 v249, v193, 4, v195
	v_add_u32_e32 v213, 0xcc00, v212
	v_add_u32_e32 v215, 0xcc00, v214
	v_add_u32_e32 v217, 0xcc00, v216
	v_add_u32_e32 v234, 0xcc00, v233
	v_add_u32_e32 v236, 0xcc00, v235
	v_add_u32_e32 v243, 0xcc00, v237
	v_add_u32_e32 v223, 0xcc00, v219
	v_add_u32_e32 v224, 0xcc00, v220
	v_add_u32_e32 v225, 0xcc00, v221
	v_add_u32_e32 v226, 0xcc00, v222
	v_add_u32_e32 v246, 0xcc00, v244
	v_add_u32_e32 v247, 0xcc00, v245
	v_lshlrev_b32_e32 v170, 2, v187
	v_add_u32_e32 v171, 0, v170
	v_cmp_le_u32_e64 s[14:15], v171, v186
	v_add_u32_e32 v171, 1, v170
	v_cmp_le_u32_e64 s[16:17], v171, v186
	v_add_u32_e32 v171, 2, v170
	v_cmp_le_u32_e64 s[22:23], v171, v186
	v_add_u32_e32 v171, 3, v170
	v_cmp_le_u32_e64 s[34:35], v171, v186
	v_lshlrev_b32_e32 v211, 9, v186
	v_lshl_add_u32 v211, v194, 7, v211
	v_lshl_add_u32 v211, v187, 4, v211
	s_cmp_eq_u32 s24, 0
	s_cselect_b32 s60, 1, 0
	s_add_u32 s39, s60, 64
	s_mov_b32 s18, s2

; __device__ __forceinline__ void phase_ssd(const Params& P, int seg, unsigned char* smem) {
;     ...
;               for (int i = 0; i < 2; ++i) { const int q = tid + 512 * i, l = q >> 4, c8 = q & 15; *(v4u*)(sb + T_CS + l * 272 + c8 * 16) = R.Cr[i]; *(v4u*)(sb + T_BS + l * 272 + c8 * 16) = R.Br[i]; }
;               const int l = tid >> 3, p4 = (tid & 7) * 4;
;               const float x0 = bflo(R.Xr.x) * R.dtl, x1 = bfhi(R.Xr.x) * R.dtl, x2 = bflo(R.Xr.y) * R.dtl, x3 = bfhi(R.Xr.y) * R.dtl;
;               v2u d; d.x = cvt_pk_bf16(x0, x1); d.y = cvt_pk_bf16(x2, x3); *(v2u*)(sb + T_XD + l * 80 + p4 * 2) = d;
;               v2u e; e.x = cvt_pk_bf16(x0 * e2, x1 * e2); e.y = cvt_pk_bf16(x2 * e2, x3 * e2); *(v2u*)(sb + T_XE + l * 80 + p4 * 2) = e;
;               *(v2u*)(sb + T_XS + l * 64 + p4 * 2) = R.Xr; *(v2u*)(sb + T_ZS + l * 64 + p4 * 2) = R.Zr;
;               if (w == 0) acP[lane] = R.aclane; }
;             BAR_LDS();
;             if (ci + 2 < nchunks) load_chunk(ci + 2, R);
;             bf16x8 cf[4];
; #pragma unroll
;             for (int k = 0; k < 4; ++k) cf[k] = *(const bf16x8*)(sb + T_CS + (lt * 16 + fr) * 272 + (k * 32 + fq * 8) * 2);
;             f32x4 yo = {0.f, 0.f, 0.f, 0.f};
; #pragma unroll
;             for (int k = 0; k < 4; ++k) { const bf16x8 bb = *(const bf16x8*)((const unsigned char*)StR + (pt * 16 + fr) * 272 + (k * 32 + fq * 8) * 2); yo = mfma16(cf[k], bb, yo); }
; { const f32x4 a4 = *(const f32x4*)(acP + lt * 16 + fq * 4);
; #pragma unroll
;               for (int j = 0; j < 4; ++j) yo[j] *= __expf(a4[j]); }
;             const float acl_fr = acP[lt * 16 + fr]; const int lrow = lt * 16 + fr;
; #pragma unroll
;             for (int t = 0; t < 2; ++t) {
;                 if (2 * t <= lt) {
;                     v2u xb0, xb1;
;                     { const unsigned a0 = lds0 + par * T_BUF + T_XD + (32 * t + 4 * fq + tq) * 80 + (pt * 16 + 4 * tp) * 2, a1 = a0 + 16 * 80; TR_ISSUE(xb0, a0); TR_ISSUE(xb1, a1); }
;                     float m[8];
;                     { f32x4 s0 = {0.f, 0.f, 0.f, 0.f}, s1 = {0.f, 0.f, 0.f, 0.f};
; #pragma unroll
;                       for (int k = 0; k < 4; ++k) { const bf16x8 bf0 = *(const bf16x8*)(sb + T_BS + ((2 * t) * 16 + fr) * 272 + (k * 32 + fq * 8) * 2), bf1 = *(const bf16x8*)(sb + T_BS + ((2 * t + 1) * 16 + fr) * 272 + (k * 32 + fq * 8) * 2);
.Lssd_loop0:
	ds_read_b128 v[28:31], v219
	ds_read_b128 v[48:51], v227
	ds_read_b128 v[32:35], v220
	ds_read_b128 v[52:55], v228
	ds_read_b128 v[40:43], v221
	ds_read_b128 v[56:59], v229
	ds_read_b128 v[44:47], v222
	ds_read_b128 v[60:63], v230
	ds_read_b32 v194, v231
	ds_read_b64_tr_b16 v[96:97], v244 offset:16384
	ds_read_b64_tr_b16 v[98:99], v244 offset:20480
	ds_read_b64_tr_b16 v[100:101], v244 offset:24576
	ds_read_b64_tr_b16 v[102:103], v244 offset:28672
	ds_read_b64_tr_b16 v[104:105], v245 offset:16384
	ds_read_b64_tr_b16 v[106:107], v245 offset:20480
	s_waitcnt lgkmcnt(11)
	ds_read_b64_tr_b16 v[108:109], v245 offset:24576
	ds_read_b64_tr_b16 v[110:111], v245 offset:28672
	ds_read_b64_tr_b16 v[112:113], v237 offset:37888
	ds_read_b64_tr_b16 v[114:115], v237 offset:39168
	s_waitcnt lgkmcnt(11)
	ds_read_b64_tr_b16 v[124:125], v237 offset:37920
	ds_read_b64_tr_b16 v[126:127], v237 offset:39200
	ds_read_b64_tr_b16 v[120:121], v237 offset:40448
	ds_read_b64_tr_b16 v[122:123], v237 offset:41728
	global_load_dwordx4 v[140:143], v204, s[40:41] offset:2048
	s_waitcnt lgkmcnt(11)
	ds_read_b64_tr_b16 v[128:129], v237 offset:40480
	ds_read_b64_tr_b16 v[130:131], v237 offset:41760
	ds_read_b128 v[64:67], v219 offset:16384
	ds_read_b128 v[68:71], v220 offset:16384
	s_waitcnt lgkmcnt(11)
	ds_read_b128 v[72:75], v221 offset:16384
	global_load_dwordx4 v[144:147], v205, s[40:41] offset:2048
	ds_read_b128 v[76:79], v222 offset:16384
	v_mfma_f32_16x16x32_bf16 v[24:27], v[48:51], v[28:31], 0
	v_mfma_f32_16x16x32_bf16 v[188:191], v[52:55], v[32:35], 0
	v_mfma_f32_16x16x32_bf16 v[24:27], v[56:59], v[40:43], v[24:27]
	v_mfma_f32_16x16x32_bf16 v[188:191], v[60:63], v[44:47], v[188:191]
	ds_read_b64_tr_b16 v[56:57], v233 offset:32768
	global_load_dwordx4 v[132:135], v204, s[40:41]
	ds_read_b64_tr_b16 v[58:59], v233 offset:34048
	v_mul_f32_e32 v8, v8, v174
	v_mul_f32_e32 v9, v9, v174
	v_mul_f32_e32 v10, v10, v174
	v_mul_f32_e32 v11, v11, v174
	global_load_dwordx4 v[136:139], v205, s[40:41]
	v_mul_f32_e32 v12, v12, v174
	v_mul_f32_e32 v13, v13, v174
	v_mul_f32_e32 v14, v14, v174
	v_mul_f32_e32 v15, v15, v174
	v_mul_f32_e32 v16, v16, v174
	v_mul_f32_e32 v17, v17, v174
	global_load_dwordx2 v[4:5], v206, s[40:41]
	v_mul_f32_e32 v18, v18, v174
	v_mul_f32_e32 v19, v19, v174
	v_mul_f32_e32 v20, v20, v174
	v_mul_f32_e32 v21, v21, v174
	v_mul_f32_e32 v22, v22, v174
	global_load_dwordx2 v[36:37], v207, s[42:43] nt
	v_mul_f32_e32 v23, v23, v174
	s_waitcnt lgkmcnt(12)
	v_mfma_f32_16x16x32_bf16 v[8:11], v[96:99], v[112:115], v[8:11]
	s_waitcnt lgkmcnt(10)
	v_mfma_f32_16x16x32_bf16 v[12:15], v[96:99], v[124:127], v[12:15]
	v_mfma_f32_16x16x32_bf16 v[16:19], v[104:107], v[112:115], v[16:19]
	v_mfma_f32_16x16x32_bf16 v[20:23], v[104:107], v[124:127], v[20:23]
	s_waitcnt lgkmcnt(8)
	v_mfma_f32_16x16x32_bf16 v[8:11], v[100:103], v[120:123], v[8:11]
	global_load_dword v6, v208, s[44:45]
	s_waitcnt lgkmcnt(6)
	v_mfma_f32_16x16x32_bf16 v[12:15], v[100:103], v[128:131], v[12:15]
	v_mfma_f32_16x16x32_bf16 v[16:19], v[108:111], v[120:123], v[16:19]
	v_mfma_f32_16x16x32_bf16 v[20:23], v[108:111], v[128:131], v[20:23]
	ds_read_b128 v[96:99], v232
	ds_read_b64 v[124:125], v235 offset:43008
	global_load_dword v116, v208, s[46:47]
	ds_read_b64 v[126:127], v235 offset:47616
	s_waitcnt lgkmcnt(8)
	v_mfma_f32_16x16x32_bf16 v[48:51], v[64:67], v[28:31], 0
	s_waitcnt lgkmcnt(7)
	v_mfma_f32_16x16x32_bf16 v[48:51], v[68:71], v[32:35], v[48:51]
	s_waitcnt lgkmcnt(6)
	v_mfma_f32_16x16x32_bf16 v[48:51], v[72:75], v[40:43], v[48:51]
	s_waitcnt lgkmcnt(5)
	v_mfma_f32_16x16x32_bf16 v[48:51], v[76:79], v[44:47], v[48:51]
	v_exp_f32_e32 v195, v194
	global_load_dword v117, v209, s[46:47]
	v_add_f32_e32 v24, v24, v188
	v_add_f32_e32 v25, v25, v189
	v_add_f32_e32 v26, v26, v190
	v_add_f32_e32 v27, v27, v191
	v_mul_f32_e32 v24, v24, v195
	s_add_u32 s66, s54, 3
	s_cmp_lt_u32 s66, s39
	s_cselect_b32 s74, 0xc0000, 0
	s_cselect_b32 s75, 0x280000, 0
	s_cselect_b32 s76, 0x4000, 0
	s_add_u32 s40, s40, s74
	s_addc_u32 s41, s41, 0
	s_add_u32 s42, s42, s75
	s_addc_u32 s43, s43, 0
	s_add_u32 s44, s44, s76
	s_addc_u32 s45, s45, 0
	s_add_u32 s46, s46, s76
	s_addc_u32 s47, s47, 0
	v_mul_f32_e32 v25, v25, v195
	v_mul_f32_e32 v26, v26, v195
	s_waitcnt vmcnt(10)
	v_mul_f32_e32 v27, v27, v195
	v_cvt_pk_bf16_f32 v184, v8, v9
	ds_write_b128 v213, v[156:159]
	v_cvt_pk_bf16_f32 v185, v10, v11
	v_cvt_pk_bf16_f32 v186, v12, v13
	ds_write_b128 v213, v[160:163] offset:8192
	v_cvt_pk_bf16_f32 v187, v14, v15
	v_cvt_pk_bf16_f32 v188, v16, v17
	ds_write_b128 v213, v[148:151] offset:16384
	v_cvt_pk_bf16_f32 v189, v18, v19
	v_cvt_pk_bf16_f32 v190, v20, v21
	ds_write_b128 v213, v[152:155] offset:24576
	v_cvt_pk_bf16_f32 v191, v22, v23
	ds_write_b64 v248, v[184:185] offset:8192
	v_sub_f32_e32 v200, v169, v168
	ds_write_b64 v248, v[186:187] offset:12288
	v_mul_f32_e32 v200, 0x3fb8aa3b, v200
	ds_write_b64 v249, v[188:189] offset:8192
	ds_write_b64 v249, v[190:191] offset:12288
	v_exp_f32_e32 v200, v200
	s_waitcnt lgkmcnt(8)
; __device__ __forceinline__ void phase_ssd(const Params& P, int seg, unsigned char* smem) {
;     ...
;               for (int i = 0; i < 2; ++i) { const int q = tid + 512 * i, l = q >> 4, c8 = q & 15; *(v4u*)(sb + T_CS + l * 272 + c8 * 16) = R.Cr[i]; *(v4u*)(sb + T_BS + l * 272 + c8 * 16) = R.Br[i]; }
;               const int l = tid >> 3, p4 = (tid & 7) * 4;
;               const float x0 = bflo(R.Xr.x) * R.dtl, x1 = bfhi(R.Xr.x) * R.dtl, x2 = bflo(R.Xr.y) * R.dtl, x3 = bfhi(R.Xr.y) * R.dtl;
;               v2u d; d.x = cvt_pk_bf16(x0, x1); d.y = cvt_pk_bf16(x2, x3); *(v2u*)(sb + T_XD + l * 80 + p4 * 2) = d;
;               v2u e; e.x = cvt_pk_bf16(x0 * e2, x1 * e2); e.y = cvt_pk_bf16(x2 * e2, x3 * e2); *(v2u*)(sb + T_XE + l * 80 + p4 * 2) = e;
;               *(v2u*)(sb + T_XS + l * 64 + p4 * 2) = R.Xr; *(v2u*)(sb + T_ZS + l * 64 + p4 * 2) = R.Zr;
;               if (w == 0) acP[lane] = R.aclane; }
;             BAR_LDS();
;             if (ci + 2 < nchunks) load_chunk(ci + 2, R);
;             bf16x8 cf[4];
; #pragma unroll
;             for (int k = 0; k < 4; ++k) cf[k] = *(const bf16x8*)(sb + T_CS + (lt * 16 + fr) * 272 + (k * 32 + fq * 8) * 2);
;             f32x4 yo = {0.f, 0.f, 0.f, 0.f};
; #pragma unroll
;             for (int k = 0; k < 4; ++k) { const bf16x8 bb = *(const bf16x8*)((const unsigned char*)StR + (pt * 16 + fr) * 272 + (k * 32 + fq * 8) * 2); yo = mfma16(cf[k], bb, yo); }
; { const f32x4 a4 = *(const f32x4*)(acP + lt * 16 + fq * 4);
; #pragma unroll
;               for (int j = 0; j < 4; ++j) yo[j] *= __expf(a4[j]); }
;             const float acl_fr = acP[lt * 16 + fr]; const int lrow = lt * 16 + fr;
; #pragma unroll
;             for (int t = 0; t < 2; ++t) {
;                 if (2 * t <= lt) {
;                     v2u xb0, xb1;
;                     { const unsigned a0 = lds0 + par * T_BUF + T_XD + (32 * t + 4 * fq + tq) * 80 + (pt * 16 + 4 * tp) * 2, a1 = a0 + 16 * 80; TR_ISSUE(xb0, a0); TR_ISSUE(xb1, a1); }
;                     float m[8];
;                     { f32x4 s0 = {0.f, 0.f, 0.f, 0.f}, s1 = {0.f, 0.f, 0.f, 0.f};
; #pragma unroll
;                       for (int k = 0; k < 4; ++k) { const bf16x8 bf0 = *(const bf16x8*)(sb + T_BS + ((2 * t) * 16 + fr) * 272 + (k * 32 + fq * 8) * 2), bf1 = *(const bf16x8*)(sb + T_BS + ((2 * t + 1) * 16 + fr) * 272 + (k * 32 + fq * 8) * 2);
	v_lshlrev_b32_e32 v112, 16, v126
	v_and_b32_e32 v113, 0xffff0000, v126
	v_lshlrev_b32_e32 v196, 16, v164
	v_lshlrev_b32_e32 v114, 16, v127
	v_and_b32_e32 v115, 0xffff0000, v127
	v_and_b32_e32 v197, 0xffff0000, v164
	v_mul_f32_e32 v120, 0xbfb8aa3b, v112
	v_mul_f32_e32 v121, 0xbfb8aa3b, v113
	v_lshlrev_b32_e32 v198, 16, v165
	v_mul_f32_e32 v122, 0xbfb8aa3b, v114
	v_mul_f32_e32 v123, 0xbfb8aa3b, v115
	v_and_b32_e32 v199, 0xffff0000, v165
	v_exp_f32_e32 v120, v120
	v_exp_f32_e32 v121, v121
	v_mul_f32_e32 v196, v196, v118
	v_exp_f32_e32 v122, v122
	v_mul_f32_e32 v197, v197, v118
	v_exp_f32_e32 v123, v123
	v_add_f32_e32 v120, 1.0, v120
	v_mul_f32_e32 v198, v198, v118
	v_add_f32_e32 v121, 1.0, v121
	v_add_f32_e32 v122, 1.0, v122
	v_mul_f32_e32 v199, v199, v118
	v_add_f32_e32 v123, 1.0, v123
	v_rcp_f32_e32 v120, v120
	v_cvt_pk_bf16_f32 v202, v196, v197
	v_rcp_f32_e32 v121, v121
	v_rcp_f32_e32 v122, v122
	v_cvt_pk_bf16_f32 v203, v198, v199
	v_rcp_f32_e32 v123, v123
	v_mul_f32_e32 v112, v120, v112
	ds_write_b64 v215, v[202:203] offset:32768
	v_mul_f32_e32 v113, v121, v113
	v_mul_f32_e32 v196, v196, v200
	v_mul_f32_e32 v114, v122, v114
	v_mul_f32_e32 v115, v123, v115
	v_mul_f32_e32 v197, v197, v200
	v_lshlrev_b32_e32 v120, 16, v124
	v_and_b32_e32 v121, 0xffff0000, v124
	v_mul_f32_e32 v198, v198, v200
	v_lshlrev_b32_e32 v122, 16, v125
	v_and_b32_e32 v123, 0xffff0000, v125
	v_mul_f32_e32 v199, v199, v200
	v_sub_f32_e32 v184, v194, v96
	v_sub_f32_e32 v185, v194, v97
	v_cvt_pk_bf16_f32 v192, v196, v197
	v_sub_f32_e32 v186, v194, v98
	v_sub_f32_e32 v187, v194, v99
	v_cvt_pk_bf16_f32 v193, v198, v199
	v_exp_f32_e32 v184, v184
	v_exp_f32_e32 v185, v185
	ds_write_b64 v215, v[192:193] offset:37888
	v_exp_f32_e32 v186, v186
	ds_write_b64 v217, v[164:165] offset:43008
	v_exp_f32_e32 v187, v187
	v_mul_f32_e32 v184, v48, v184
	ds_write_b64 v217, v[166:167] offset:47616
	v_mul_f32_e32 v185, v49, v185
	v_mul_f32_e32 v186, v50, v186
	v_mul_f32_e32 v201, 0x3fb8aa3b, v168
	v_mul_f32_e32 v187, v51, v187
	v_cndmask_b32_e64 v184, 0, v184, s[14:15]
	ds_write_b32 v218, v201 offset:256
	v_cndmask_b32_e64 v185, 0, v185, s[16:17]
	v_cndmask_b32_e64 v186, 0, v186, s[22:23]
	v_mul_f32_e32 v174, 0x3fb8aa3b, v169
	v_cndmask_b32_e64 v187, 0, v187, s[34:35]
	v_cvt_pk_bf16_f32 v128, v184, v185
	v_exp_f32_e32 v174, v174
	v_cvt_pk_bf16_f32 v129, v186, v187
	v_mov_b32_e32 v130, 0
	v_mov_b32_e32 v131, 0
	s_nop 1
	v_mfma_f32_16x16x32_bf16 v[24:27], v[56:59], v[128:131], v[24:27]
	s_mul_i32 s65, s56, 0x2000
	s_add_u32 s65, s65, 0x304f1000
	s_add_u32 s48, s0, s65
	s_addc_u32 s49, s1, 0
	s_nop 3
	v_fma_f32 v184, s61, v120, v24
	v_fma_f32 v185, s61, v121, v25
	v_fma_f32 v186, s61, v122, v26
	v_fma_f32 v187, s61, v123, v27
	v_mul_f32_e32 v184, v184, v112
	v_mul_f32_e32 v185, v185, v113
	v_mul_f32_e32 v186, v186, v114
	v_mul_f32_e32 v187, v187, v115
	v_cvt_pk_bf16_f32 v170, v184, v185
	v_cvt_pk_bf16_f32 v171, v186, v187
	global_store_dwordx2 v210, v[170:171], s[48:49]
	s_add_u32 s65, s54, 1
	s_sub_u32 s65, s65, s60
	s_lshl_b32 s65, s65, 6
	s_add_u32 s56, s65, s20
	s_waitcnt lgkmcnt(0)
	s_barrier
	s_add_u32 s54, s54, 1
	s_cmp_ge_u32 s54, s39
	s_cbranch_scc1 .Lssd_done
	ds_read_b128 v[28:31], v223
	ds_read_b128 v[48:51], v227 offset:8192
	ds_read_b128 v[32:35], v224
	ds_read_b128 v[52:55], v228 offset:8192
	ds_read_b128 v[40:43], v225
	ds_read_b128 v[56:59], v229 offset:8192
	ds_read_b128 v[44:47], v226
	ds_read_b128 v[60:63], v230 offset:8192
	ds_read_b32 v194, v231 offset:256
	ds_read_b64_tr_b16 v[96:97], v246 offset:16384
	ds_read_b64_tr_b16 v[98:99], v246 offset:20480
	ds_read_b64_tr_b16 v[100:101], v246 offset:24576
	ds_read_b64_tr_b16 v[102:103], v246 offset:28672
	ds_read_b64_tr_b16 v[104:105], v247 offset:16384
	ds_read_b64_tr_b16 v[106:107], v247 offset:20480
	s_waitcnt lgkmcnt(11)
	ds_read_b64_tr_b16 v[108:109], v247 offset:24576
	ds_read_b64_tr_b16 v[110:111], v247 offset:28672
	ds_read_b64_tr_b16 v[112:113], v243 offset:37888
	ds_read_b64_tr_b16 v[114:115], v243 offset:39168
	s_waitcnt lgkmcnt(11)
	ds_read_b64_tr_b16 v[124:125], v243 offset:37920
	ds_read_b64_tr_b16 v[126:127], v243 offset:39200
	ds_read_b64_tr_b16 v[120:121], v243 offset:40448
	ds_read_b64_tr_b16 v[122:123], v243 offset:41728
	global_load_dwordx4 v[156:159], v204, s[40:41] offset:2048
	s_waitcnt lgkmcnt(11)
	ds_read_b64_tr_b16 v[128:129], v243 offset:40480
	ds_read_b64_tr_b16 v[130:131], v243 offset:41760
	ds_read_b128 v[64:67], v223 offset:16384
	ds_read_b128 v[68:71], v224 offset:16384
	s_waitcnt lgkmcnt(11)
	ds_read_b128 v[72:75], v225 offset:16384
	global_load_dwordx4 v[160:163], v205, s[40:41] offset:2048
	ds_read_b128 v[76:79], v226 offset:16384
	v_mfma_f32_16x16x32_bf16 v[24:27], v[48:51], v[28:31], 0
	v_mfma_f32_16x16x32_bf16 v[188:191], v[52:55], v[32:35], 0
	v_mfma_f32_16x16x32_bf16 v[24:27], v[56:59], v[40:43], v[24:27]
	v_mfma_f32_16x16x32_bf16 v[188:191], v[60:63], v[44:47], v[188:191]
	ds_read_b64_tr_b16 v[56:57], v234 offset:32768
	global_load_dwordx4 v[148:151], v204, s[40:41]
	ds_read_b64_tr_b16 v[58:59], v234 offset:34048
	v_mul_f32_e32 v8, v8, v174
	v_mul_f32_e32 v9, v9, v174
	v_mul_f32_e32 v10, v10, v174
	v_mul_f32_e32 v11, v11, v174
	global_load_dwordx4 v[152:155], v205, s[40:41]
	v_mul_f32_e32 v12, v12, v174
	v_mul_f32_e32 v13, v13, v174
	v_mul_f32_e32 v14, v14, v174
	v_mul_f32_e32 v15, v15, v174
	v_mul_f32_e32 v16, v16, v174
	v_mul_f32_e32 v17, v17, v174
	global_load_dwordx2 v[164:165], v206, s[40:41]
	v_mul_f32_e32 v18, v18, v174
	v_mul_f32_e32 v19, v19, v174
	v_mul_f32_e32 v20, v20, v174
	v_mul_f32_e32 v21, v21, v174
	v_mul_f32_e32 v22, v22, v174
	global_load_dwordx2 v[166:167], v207, s[42:43] nt
	v_mul_f32_e32 v23, v23, v174
	s_waitcnt lgkmcnt(12)
; __device__ __forceinline__ void phase_ssd(const Params& P, int seg, unsigned char* smem) {
;     ...
;               for (int i = 0; i < 2; ++i) { const int q = tid + 512 * i, l = q >> 4, c8 = q & 15; *(v4u*)(sb + T_CS + l * 272 + c8 * 16) = R.Cr[i]; *(v4u*)(sb + T_BS + l * 272 + c8 * 16) = R.Br[i]; }
;               const int l = tid >> 3, p4 = (tid & 7) * 4;
;               const float x0 = bflo(R.Xr.x) * R.dtl, x1 = bfhi(R.Xr.x) * R.dtl, x2 = bflo(R.Xr.y) * R.dtl, x3 = bfhi(R.Xr.y) * R.dtl;
;               v2u d; d.x = cvt_pk_bf16(x0, x1); d.y = cvt_pk_bf16(x2, x3); *(v2u*)(sb + T_XD + l * 80 + p4 * 2) = d;
;               v2u e; e.x = cvt_pk_bf16(x0 * e2, x1 * e2); e.y = cvt_pk_bf16(x2 * e2, x3 * e2); *(v2u*)(sb + T_XE + l * 80 + p4 * 2) = e;
;               *(v2u*)(sb + T_XS + l * 64 + p4 * 2) = R.Xr; *(v2u*)(sb + T_ZS + l * 64 + p4 * 2) = R.Zr;
;               if (w == 0) acP[lane] = R.aclane; }
;             BAR_LDS();
;             if (ci + 2 < nchunks) load_chunk(ci + 2, R);
;             bf16x8 cf[4];
; #pragma unroll
;             for (int k = 0; k < 4; ++k) cf[k] = *(const bf16x8*)(sb + T_CS + (lt * 16 + fr) * 272 + (k * 32 + fq * 8) * 2);
;             f32x4 yo = {0.f, 0.f, 0.f, 0.f};
; #pragma unroll
;             for (int k = 0; k < 4; ++k) { const bf16x8 bb = *(const bf16x8*)((const unsigned char*)StR + (pt * 16 + fr) * 272 + (k * 32 + fq * 8) * 2); yo = mfma16(cf[k], bb, yo); }
; { const f32x4 a4 = *(const f32x4*)(acP + lt * 16 + fq * 4);
; #pragma unroll
;               for (int j = 0; j < 4; ++j) yo[j] *= __expf(a4[j]); }
;             const float acl_fr = acP[lt * 16 + fr]; const int lrow = lt * 16 + fr;
; #pragma unroll
;             for (int t = 0; t < 2; ++t) {
;                 if (2 * t <= lt) {
;                     v2u xb0, xb1;
;                     { const unsigned a0 = lds0 + par * T_BUF + T_XD + (32 * t + 4 * fq + tq) * 80 + (pt * 16 + 4 * tp) * 2, a1 = a0 + 16 * 80; TR_ISSUE(xb0, a0); TR_ISSUE(xb1, a1); }
;                     float m[8];
;                     { f32x4 s0 = {0.f, 0.f, 0.f, 0.f}, s1 = {0.f, 0.f, 0.f, 0.f};
; #pragma unroll
;                       for (int k = 0; k < 4; ++k) { const bf16x8 bf0 = *(const bf16x8*)(sb + T_BS + ((2 * t) * 16 + fr) * 272 + (k * 32 + fq * 8) * 2), bf1 = *(const bf16x8*)(sb + T_BS + ((2 * t + 1) * 16 + fr) * 272 + (k * 32 + fq * 8) * 2);
	v_mfma_f32_16x16x32_bf16 v[8:11], v[96:99], v[112:115], v[8:11]
	s_waitcnt lgkmcnt(10)
	v_mfma_f32_16x16x32_bf16 v[12:15], v[96:99], v[124:127], v[12:15]
	v_mfma_f32_16x16x32_bf16 v[16:19], v[104:107], v[112:115], v[16:19]
	v_mfma_f32_16x16x32_bf16 v[20:23], v[104:107], v[124:127], v[20:23]
	s_waitcnt lgkmcnt(8)
	v_mfma_f32_16x16x32_bf16 v[8:11], v[100:103], v[120:123], v[8:11]
	global_load_dword v118, v208, s[44:45]
	s_waitcnt lgkmcnt(6)
	v_mfma_f32_16x16x32_bf16 v[12:15], v[100:103], v[128:131], v[12:15]
	v_mfma_f32_16x16x32_bf16 v[16:19], v[108:111], v[120:123], v[16:19]
	v_mfma_f32_16x16x32_bf16 v[20:23], v[108:111], v[128:131], v[20:23]
	ds_read_b128 v[96:99], v232 offset:256
	ds_read_b64 v[124:125], v236 offset:43008
	global_load_dword v168, v208, s[46:47]
	ds_read_b64 v[126:127], v236 offset:47616
	s_waitcnt lgkmcnt(8)
	v_mfma_f32_16x16x32_bf16 v[48:51], v[64:67], v[28:31], 0
	s_waitcnt lgkmcnt(7)
	v_mfma_f32_16x16x32_bf16 v[48:51], v[68:71], v[32:35], v[48:51]
	s_waitcnt lgkmcnt(6)
	v_mfma_f32_16x16x32_bf16 v[48:51], v[72:75], v[40:43], v[48:51]
	s_waitcnt lgkmcnt(5)
	v_mfma_f32_16x16x32_bf16 v[48:51], v[76:79], v[44:47], v[48:51]
	v_exp_f32_e32 v195, v194
	global_load_dword v169, v209, s[46:47]
	v_add_f32_e32 v24, v24, v188
	v_add_f32_e32 v25, v25, v189
	v_add_f32_e32 v26, v26, v190
	v_add_f32_e32 v27, v27, v191
	v_mul_f32_e32 v24, v24, v195
	s_add_u32 s66, s54, 3
	s_cmp_lt_u32 s66, s39
	s_cselect_b32 s74, 0xc0000, 0
	s_cselect_b32 s75, 0x280000, 0
	s_cselect_b32 s76, 0x4000, 0
	s_add_u32 s40, s40, s74
	s_addc_u32 s41, s41, 0
	s_add_u32 s42, s42, s75
	s_addc_u32 s43, s43, 0
	s_add_u32 s44, s44, s76
	s_addc_u32 s45, s45, 0
	s_add_u32 s46, s46, s76
	s_addc_u32 s47, s47, 0
	v_mul_f32_e32 v25, v25, v195
	v_mul_f32_e32 v26, v26, v195
	s_waitcnt vmcnt(10)
	v_mul_f32_e32 v27, v27, v195
	v_cvt_pk_bf16_f32 v184, v8, v9
	ds_write_b128 v212, v[140:143]
	v_cvt_pk_bf16_f32 v185, v10, v11
	v_cvt_pk_bf16_f32 v186, v12, v13
	ds_write_b128 v212, v[144:147] offset:8192
	v_cvt_pk_bf16_f32 v187, v14, v15
	v_cvt_pk_bf16_f32 v188, v16, v17
	ds_write_b128 v212, v[132:135] offset:16384
	v_cvt_pk_bf16_f32 v189, v18, v19
	v_cvt_pk_bf16_f32 v190, v20, v21
	ds_write_b128 v212, v[136:139] offset:24576
	v_cvt_pk_bf16_f32 v191, v22, v23
	ds_write_b64 v248, v[184:185]
	v_sub_f32_e32 v200, v117, v116
	ds_write_b64 v248, v[186:187] offset:4096
	v_mul_f32_e32 v200, 0x3fb8aa3b, v200
	ds_write_b64 v249, v[188:189]
	ds_write_b64 v249, v[190:191] offset:4096
	v_exp_f32_e32 v200, v200
	s_waitcnt lgkmcnt(8)
	v_lshlrev_b32_e32 v112, 16, v126
	v_and_b32_e32 v113, 0xffff0000, v126
	v_lshlrev_b32_e32 v196, 16, v4
	v_lshlrev_b32_e32 v114, 16, v127
	v_and_b32_e32 v115, 0xffff0000, v127
	v_and_b32_e32 v197, 0xffff0000, v4
	v_mul_f32_e32 v120, 0xbfb8aa3b, v112
	v_mul_f32_e32 v121, 0xbfb8aa3b, v113
	v_lshlrev_b32_e32 v198, 16, v5
	v_mul_f32_e32 v122, 0xbfb8aa3b, v114
	v_mul_f32_e32 v123, 0xbfb8aa3b, v115
	v_and_b32_e32 v199, 0xffff0000, v5
	v_exp_f32_e32 v120, v120
	v_exp_f32_e32 v121, v121
	v_mul_f32_e32 v196, v196, v6
	v_exp_f32_e32 v122, v122
	v_mul_f32_e32 v197, v197, v6
	v_exp_f32_e32 v123, v123
	v_add_f32_e32 v120, 1.0, v120
	v_mul_f32_e32 v198, v198, v6
	v_add_f32_e32 v121, 1.0, v121
	v_add_f32_e32 v122, 1.0, v122
	v_mul_f32_e32 v199, v199, v6
	v_add_f32_e32 v123, 1.0, v123
	v_rcp_f32_e32 v120, v120
	v_cvt_pk_bf16_f32 v202, v196, v197
	v_rcp_f32_e32 v121, v121
	v_rcp_f32_e32 v122, v122
	v_cvt_pk_bf16_f32 v203, v198, v199
	v_rcp_f32_e32 v123, v123
	v_mul_f32_e32 v112, v120, v112
	ds_write_b64 v214, v[202:203] offset:32768
	v_mul_f32_e32 v113, v121, v113
	v_mul_f32_e32 v196, v196, v200
	v_mul_f32_e32 v114, v122, v114
	v_mul_f32_e32 v115, v123, v115
	v_mul_f32_e32 v197, v197, v200
	v_lshlrev_b32_e32 v120, 16, v124
	v_and_b32_e32 v121, 0xffff0000, v124
	v_mul_f32_e32 v198, v198, v200
	v_lshlrev_b32_e32 v122, 16, v125
	v_and_b32_e32 v123, 0xffff0000, v125
	v_mul_f32_e32 v199, v199, v200
	v_sub_f32_e32 v184, v194, v96
	v_sub_f32_e32 v185, v194, v97
	v_cvt_pk_bf16_f32 v192, v196, v197
	v_sub_f32_e32 v186, v194, v98
	v_sub_f32_e32 v187, v194, v99
	v_cvt_pk_bf16_f32 v193, v198, v199
	v_exp_f32_e32 v184, v184
	v_exp_f32_e32 v185, v185
	ds_write_b64 v214, v[192:193] offset:37888
	v_exp_f32_e32 v186, v186
	ds_write_b64 v216, v[4:5] offset:43008
	v_exp_f32_e32 v187, v187
	v_mul_f32_e32 v184, v48, v184
	ds_write_b64 v216, v[36:37] offset:47616
	v_mul_f32_e32 v185, v49, v185
	v_mul_f32_e32 v186, v50, v186
	v_mul_f32_e32 v201, 0x3fb8aa3b, v116
	v_mul_f32_e32 v187, v51, v187
	v_cndmask_b32_e64 v184, 0, v184, s[14:15]
	ds_write_b32 v218, v201
	v_cndmask_b32_e64 v185, 0, v185, s[16:17]
	v_cndmask_b32_e64 v186, 0, v186, s[22:23]
	v_mul_f32_e32 v174, 0x3fb8aa3b, v117
	v_cndmask_b32_e64 v187, 0, v187, s[34:35]
	v_cvt_pk_bf16_f32 v128, v184, v185
	v_exp_f32_e32 v174, v174
	v_cvt_pk_bf16_f32 v129, v186, v187
	v_mov_b32_e32 v130, 0
	v_mov_b32_e32 v131, 0
	s_nop 1
	v_mfma_f32_16x16x32_bf16 v[24:27], v[56:59], v[128:131], v[24:27]
	s_mul_i32 s65, s56, 0x2000
	s_add_u32 s65, s65, 0x304f1000
	s_add_u32 s48, s0, s65
	s_addc_u32 s49, s1, 0
	s_nop 3
	v_fma_f32 v184, s61, v120, v24
	v_fma_f32 v185, s61, v121, v25
	v_fma_f32 v186, s61, v122, v26
	v_fma_f32 v187, s61, v123, v27
	v_mul_f32_e32 v184, v184, v112
	v_mul_f32_e32 v185, v185, v113
	v_mul_f32_e32 v186, v186, v114
	v_mul_f32_e32 v187, v187, v115
	v_cvt_pk_bf16_f32 v170, v184, v185
	v_cvt_pk_bf16_f32 v171, v186, v187
	global_store_dwordx2 v210, v[170:171], s[48:49]
	s_add_u32 s65, s54, 1
	s_sub_u32 s65, s65, s60
	s_lshl_b32 s65, s65, 6
	s_add_u32 s56, s65, s20
	s_waitcnt lgkmcnt(0)
	s_barrier
	s_add_u32 s54, s54, 1
	s_cmp_lt_u32 s54, s39
	s_cbranch_scc1 .Lssd_loop0
	s_branch .Lssd_done
; __device__ __forceinline__ void phase_ssd(const Params& P, int seg, unsigned char* smem) {
;     ...
;             bf16x8 cf[4];
; #pragma unroll
;             for (int k = 0; k < 4; ++k) cf[k] = *(const bf16x8*)(sb + T_CS + (lt * 16 + fr) * 272 + (k * 32 + fq * 8) * 2);
;             f32x4 yo = {0.f, 0.f, 0.f, 0.f};
; #pragma unroll
;             for (int k = 0; k < 4; ++k) { const bf16x8 bb = *(const bf16x8*)((const unsigned char*)StR + (pt * 16 + fr) * 272 + (k * 32 + fq * 8) * 2); yo = mfma16(cf[k], bb, yo); }
; { const f32x4 a4 = *(const f32x4*)(acP + lt * 16 + fq * 4);
; #pragma unroll
;               for (int j = 0; j < 4; ++j) yo[j] *= __expf(a4[j]); }
;             const float acl_fr = acP[lt * 16 + fr]; const int lrow = lt * 16 + fr;
; #pragma unroll
;             for (int t = 0; t < 2; ++t) {
;                 if (2 * t <= lt) {
;                     v2u xb0, xb1;
;                     { const unsigned a0 = lds0 + par * T_BUF + T_XD + (32 * t + 4 * fq + tq) * 80 + (pt * 16 + 4 * tp) * 2, a1 = a0 + 16 * 80; TR_ISSUE(xb0, a0); TR_ISSUE(xb1, a1); }
;                     float m[8];
;                     { f32x4 s0 = {0.f, 0.f, 0.f, 0.f}, s1 = {0.f, 0.f, 0.f, 0.f};
; #pragma unroll
;                       for (int k = 0; k < 4; ++k) { const bf16x8 bf0 = *(const bf16x8*)(sb + T_BS + ((2 * t) * 16 + fr) * 272 + (k * 32 + fq * 8) * 2), bf1 = *(const bf16x8*)(sb + T_BS + ((2 * t + 1) * 16 + fr) * 272 + (k * 32 + fq * 8) * 2);
;                           s0 = mfma16(bf0, cf[k], s0); s1 = mfma16(bf1, cf[k], s1); }
;                       const f32x4 a0 = *(const f32x4*)(acP + (2 * t) * 16 + fq * 4), a1 = *(const f32x4*)(acP + (2 * t + 1) * 16 + fq * 4);
; #pragma unroll
;                       for (int j = 0; j < 4; ++j) { const int si0 = (2 * t) * 16 + fq * 4 + j, si1 = si0 + 16;
;                           const float e0 = s0[j] * __expf(fminf(acl_fr - a0[j], 0.f)), e1 = s1[j] * __expf(fminf(acl_fr - a1[j], 0.f));
;                           m[j] = (si0 <= lrow) ? e0 : 0.f; m[4 + j] = (si1 <= lrow) ? e1 : 0.f; } }
;                     v4u mp; mp.x = cvt_pk_bf16(m[0], m[1]); mp.y = cvt_pk_bf16(m[2], m[3]); mp.z = cvt_pk_bf16(m[4], m[5]); mp.w = cvt_pk_bf16(m[6], m[7]);
;                     asm volatile("s_waitcnt lgkmcnt(0)" : "+v"(xb0), "+v"(xb1) :: "memory");
;                     yo = mfma16(__builtin_bit_cast(bf16x8, mp), mk8(xb0, xb1), yo);
.Lssd_loop1:
	ds_read_b128 v[28:31], v219 offset:4096
	ds_read_b128 v[48:51], v227
	ds_read_b128 v[32:35], v220 offset:4096
	ds_read_b128 v[52:55], v228
	ds_read_b128 v[40:43], v221 offset:4096
	ds_read_b128 v[56:59], v229
	ds_read_b128 v[44:47], v222 offset:4096
	ds_read_b128 v[60:63], v230
	ds_read_b32 v194, v231 offset:64
	ds_read_b64_tr_b16 v[96:97], v244 offset:16384
	ds_read_b64_tr_b16 v[98:99], v244 offset:20480
	ds_read_b64_tr_b16 v[100:101], v244 offset:24576
	ds_read_b64_tr_b16 v[102:103], v244 offset:28672
	ds_read_b64_tr_b16 v[104:105], v245 offset:16384
	ds_read_b64_tr_b16 v[106:107], v245 offset:20480
	s_waitcnt lgkmcnt(11)
	ds_read_b64_tr_b16 v[108:109], v245 offset:24576
	ds_read_b64_tr_b16 v[110:111], v245 offset:28672
	ds_read_b64_tr_b16 v[112:113], v237 offset:37888
	ds_read_b64_tr_b16 v[114:115], v237 offset:39168
	s_waitcnt lgkmcnt(11)
	ds_read_b64_tr_b16 v[124:125], v237 offset:37920
	ds_read_b64_tr_b16 v[126:127], v237 offset:39200
	ds_read_b64_tr_b16 v[120:121], v237 offset:40448
	ds_read_b64_tr_b16 v[122:123], v237 offset:41728
	s_waitcnt lgkmcnt(11)
	ds_read_b64_tr_b16 v[128:129], v237 offset:40480
	ds_read_b64_tr_b16 v[130:131], v237 offset:41760
	ds_read_b128 v[64:67], v219 offset:16384
	ds_read_b128 v[68:71], v220 offset:16384
	global_load_dwordx4 v[140:143], v204, s[40:41] offset:2048
	s_waitcnt lgkmcnt(11)
	ds_read_b128 v[72:75], v221 offset:16384
	ds_read_b128 v[76:79], v222 offset:16384
	ds_read_b128 v[80:83], v219 offset:20480
	ds_read_b128 v[84:87], v220 offset:20480
	s_waitcnt lgkmcnt(11)
	ds_read_b128 v[88:91], v221 offset:20480
	ds_read_b128 v[92:95], v222 offset:20480
	global_load_dwordx4 v[144:147], v205, s[40:41] offset:2048
	v_mfma_f32_16x16x32_bf16 v[24:27], v[48:51], v[28:31], 0
	v_mfma_f32_16x16x32_bf16 v[188:191], v[52:55], v[32:35], 0
	v_mfma_f32_16x16x32_bf16 v[24:27], v[56:59], v[40:43], v[24:27]
	v_mfma_f32_16x16x32_bf16 v[188:191], v[60:63], v[44:47], v[188:191]
	ds_read_b64_tr_b16 v[56:57], v233 offset:32768
	ds_read_b64_tr_b16 v[58:59], v233 offset:34048
	global_load_dwordx4 v[132:135], v204, s[40:41]
	v_mul_f32_e32 v8, v8, v174
	v_mul_f32_e32 v9, v9, v174
	v_mul_f32_e32 v10, v10, v174
	v_mul_f32_e32 v11, v11, v174
	v_mul_f32_e32 v12, v12, v174
	v_mul_f32_e32 v13, v13, v174
	v_mul_f32_e32 v14, v14, v174
	global_load_dwordx4 v[136:139], v205, s[40:41]
	v_mul_f32_e32 v15, v15, v174
	v_mul_f32_e32 v16, v16, v174
	v_mul_f32_e32 v17, v17, v174
	v_mul_f32_e32 v18, v18, v174
	v_mul_f32_e32 v19, v19, v174
	v_mul_f32_e32 v20, v20, v174
	global_load_dwordx2 v[4:5], v206, s[40:41]
	v_mul_f32_e32 v21, v21, v174
	v_mul_f32_e32 v22, v22, v174
	v_mul_f32_e32 v23, v23, v174
	v_mfma_f32_16x16x32_bf16 v[8:11], v[96:99], v[112:115], v[8:11]
	s_waitcnt lgkmcnt(14)
	v_mfma_f32_16x16x32_bf16 v[12:15], v[96:99], v[124:127], v[12:15]
	v_mfma_f32_16x16x32_bf16 v[16:19], v[104:107], v[112:115], v[16:19]
	v_mfma_f32_16x16x32_bf16 v[20:23], v[104:107], v[124:127], v[20:23]
	global_load_dwordx2 v[36:37], v207, s[42:43] nt
	s_waitcnt lgkmcnt(12)
	v_mfma_f32_16x16x32_bf16 v[8:11], v[100:103], v[120:123], v[8:11]
	s_waitcnt lgkmcnt(10)
	v_mfma_f32_16x16x32_bf16 v[12:15], v[100:103], v[128:131], v[12:15]
	v_mfma_f32_16x16x32_bf16 v[16:19], v[108:111], v[120:123], v[16:19]
	v_mfma_f32_16x16x32_bf16 v[20:23], v[108:111], v[128:131], v[20:23]
	ds_read_b128 v[96:99], v232
	ds_read_b128 v[100:103], v232 offset:64
	global_load_dword v6, v208, s[44:45]
	ds_read_b64 v[124:125], v235 offset:44160
	ds_read_b64 v[126:127], v235 offset:48768
	s_waitcnt lgkmcnt(13)
	v_mfma_f32_16x16x32_bf16 v[48:51], v[64:67], v[28:31], 0
	s_waitcnt lgkmcnt(9)
	v_mfma_f32_16x16x32_bf16 v[52:55], v[80:83], v[28:31], 0
	v_mfma_f32_16x16x32_bf16 v[48:51], v[68:71], v[32:35], v[48:51]
	s_waitcnt lgkmcnt(8)
	v_mfma_f32_16x16x32_bf16 v[52:55], v[84:87], v[32:35], v[52:55]
	global_load_dword v116, v208, s[46:47]
	v_mfma_f32_16x16x32_bf16 v[48:51], v[72:75], v[40:43], v[48:51]
	s_waitcnt lgkmcnt(7)
	v_mfma_f32_16x16x32_bf16 v[52:55], v[88:91], v[40:43], v[52:55]
	v_mfma_f32_16x16x32_bf16 v[48:51], v[76:79], v[44:47], v[48:51]
	s_waitcnt lgkmcnt(6)
	v_mfma_f32_16x16x32_bf16 v[52:55], v[92:95], v[44:47], v[52:55]
	v_exp_f32_e32 v195, v194
	v_add_f32_e32 v24, v24, v188
	v_add_f32_e32 v25, v25, v189
	global_load_dword v117, v209, s[46:47]
	v_add_f32_e32 v26, v26, v190
	v_add_f32_e32 v27, v27, v191
	v_mul_f32_e32 v24, v24, v195
	v_mul_f32_e32 v25, v25, v195
	v_mul_f32_e32 v26, v26, v195
	v_mul_f32_e32 v27, v27, v195
	s_add_u32 s66, s54, 3
	s_cmp_lt_u32 s66, s39
	s_cselect_b32 s74, 0xc0000, 0
	s_cselect_b32 s75, 0x280000, 0
	s_cselect_b32 s76, 0x4000, 0
	s_add_u32 s40, s40, s74
	s_addc_u32 s41, s41, 0
	s_add_u32 s42, s42, s75
	s_addc_u32 s43, s43, 0
	s_add_u32 s44, s44, s76
	s_addc_u32 s45, s45, 0
	s_add_u32 s46, s46, s76
	s_addc_u32 s47, s47, 0
	v_cvt_pk_bf16_f32 v184, v8, v9
	v_cvt_pk_bf16_f32 v185, v10, v11
	s_waitcnt vmcnt(10)
	v_cvt_pk_bf16_f32 v186, v12, v13
	v_cvt_pk_bf16_f32 v187, v14, v15
	ds_write_b128 v213, v[156:159]
	v_cvt_pk_bf16_f32 v188, v16, v17
	v_cvt_pk_bf16_f32 v189, v18, v19
	v_cvt_pk_bf16_f32 v190, v20, v21
	ds_write_b128 v213, v[160:163] offset:8192
	v_cvt_pk_bf16_f32 v191, v22, v23
	ds_write_b64 v248, v[184:185] offset:8192
	ds_write_b128 v213, v[148:151] offset:16384
	ds_write_b64 v248, v[186:187] offset:12288
	ds_write_b64 v249, v[188:189] offset:8192
	ds_write_b128 v213, v[152:155] offset:24576
	ds_write_b64 v249, v[190:191] offset:12288
	s_waitcnt lgkmcnt(8)
; __device__ __forceinline__ unsigned cvt_pk_bf16(float lo, float hi) { unsigned r; asm volatile("v_cvt_pk_bf16_f32 %0, %1, %2" : "=v"(r) : "v"(lo), "v"(hi)); return r; }
; __device__ __forceinline__ void phase_ssd(const Params& P, int seg, unsigned char* smem) {
;     ...
;             { const float e2 = __expf(R.alast - R.acl);
; #pragma unroll
;               for (int i = 0; i < 2; ++i) { const int q = tid + 512 * i, l = q >> 4, c8 = q & 15; *(v4u*)(sb + T_CS + l * 272 + c8 * 16) = R.Cr[i]; *(v4u*)(sb + T_BS + l * 272 + c8 * 16) = R.Br[i]; }
;               const int l = tid >> 3, p4 = (tid & 7) * 4;
;               const float x0 = bflo(R.Xr.x) * R.dtl, x1 = bfhi(R.Xr.x) * R.dtl, x2 = bflo(R.Xr.y) * R.dtl, x3 = bfhi(R.Xr.y) * R.dtl;
;               v2u d; d.x = cvt_pk_bf16(x0, x1); d.y = cvt_pk_bf16(x2, x3); *(v2u*)(sb + T_XD + l * 80 + p4 * 2) = d;
;               v2u e; e.x = cvt_pk_bf16(x0 * e2, x1 * e2); e.y = cvt_pk_bf16(x2 * e2, x3 * e2); *(v2u*)(sb + T_XE + l * 80 + p4 * 2) = e;
;               *(v2u*)(sb + T_XS + l * 64 + p4 * 2) = R.Xr; *(v2u*)(sb + T_ZS + l * 64 + p4 * 2) = R.Zr;
;               if (w == 0) acP[lane] = R.aclane; }
;             BAR_LDS();
;             if (ci + 2 < nchunks) load_chunk(ci + 2, R);
;             bf16x8 cf[4];
; #pragma unroll
;             for (int k = 0; k < 4; ++k) cf[k] = *(const bf16x8*)(sb + T_CS + (lt * 16 + fr) * 272 + (k * 32 + fq * 8) * 2);
;             f32x4 yo = {0.f, 0.f, 0.f, 0.f};
; #pragma unroll
;             for (int k = 0; k < 4; ++k) { const bf16x8 bb = *(const bf16x8*)((const unsigned char*)StR + (pt * 16 + fr) * 272 + (k * 32 + fq * 8) * 2); yo = mfma16(cf[k], bb, yo); }
; { const f32x4 a4 = *(const f32x4*)(acP + lt * 16 + fq * 4);
; #pragma unroll
;               for (int j = 0; j < 4; ++j) yo[j] *= __expf(a4[j]); }
;             const float acl_fr = acP[lt * 16 + fr]; const int lrow = lt * 16 + fr;
; #pragma unroll
;             for (int t = 0; t < 2; ++t) {
;                 if (2 * t <= lt) {
;                     v2u xb0, xb1;
;                     { const unsigned a0 = lds0 + par * T_BUF + T_XD + (32 * t + 4 * fq + tq) * 80 + (pt * 16 + 4 * tp) * 2, a1 = a0 + 16 * 80; TR_ISSUE(xb0, a0); TR_ISSUE(xb1, a1); }
;                     float m[8];
;                     { f32x4 s0 = {0.f, 0.f, 0.f, 0.f}, s1 = {0.f, 0.f, 0.f, 0.f};
; #pragma unroll
	v_lshlrev_b32_e32 v112, 16, v126
	v_sub_f32_e32 v200, v169, v168
	v_and_b32_e32 v113, 0xffff0000, v126
	v_lshlrev_b32_e32 v114, 16, v127
	v_mul_f32_e32 v200, 0x3fb8aa3b, v200
	v_and_b32_e32 v115, 0xffff0000, v127
	v_mul_f32_e32 v120, 0xbfb8aa3b, v112
	v_exp_f32_e32 v200, v200
	v_mul_f32_e32 v121, 0xbfb8aa3b, v113
	v_mul_f32_e32 v122, 0xbfb8aa3b, v114
	v_lshlrev_b32_e32 v196, 16, v164
	v_mul_f32_e32 v123, 0xbfb8aa3b, v115
	v_exp_f32_e32 v120, v120
	v_and_b32_e32 v197, 0xffff0000, v164
	v_exp_f32_e32 v121, v121
	v_exp_f32_e32 v122, v122
	v_exp_f32_e32 v123, v123
	v_lshlrev_b32_e32 v198, 16, v165
	v_add_f32_e32 v120, 1.0, v120
	v_add_f32_e32 v121, 1.0, v121
	v_and_b32_e32 v199, 0xffff0000, v165
	v_add_f32_e32 v122, 1.0, v122
	v_add_f32_e32 v123, 1.0, v123
	v_mul_f32_e32 v196, v196, v118
	v_rcp_f32_e32 v120, v120
	v_rcp_f32_e32 v121, v121
	v_mul_f32_e32 v197, v197, v118
	v_rcp_f32_e32 v122, v122
	v_rcp_f32_e32 v123, v123
	v_mul_f32_e32 v198, v198, v118
	v_mul_f32_e32 v112, v120, v112
	v_mul_f32_e32 v113, v121, v113
	v_mul_f32_e32 v199, v199, v118
	v_mul_f32_e32 v114, v122, v114
	v_mul_f32_e32 v115, v123, v115
	v_cvt_pk_bf16_f32 v202, v196, v197
	v_lshlrev_b32_e32 v120, 16, v124
	v_and_b32_e32 v121, 0xffff0000, v124
	v_lshlrev_b32_e32 v122, 16, v125
	v_cvt_pk_bf16_f32 v203, v198, v199
	v_and_b32_e32 v123, 0xffff0000, v125
	v_sub_f32_e32 v184, v194, v96
	ds_write_b64 v215, v[202:203] offset:32768
	v_sub_f32_e32 v185, v194, v97
	v_sub_f32_e32 v186, v194, v98
	v_mul_f32_e32 v196, v196, v200
	v_sub_f32_e32 v187, v194, v99
	v_exp_f32_e32 v184, v184
	v_mul_f32_e32 v197, v197, v200
	v_exp_f32_e32 v185, v185
	v_exp_f32_e32 v186, v186
	v_mul_f32_e32 v198, v198, v200
	v_exp_f32_e32 v187, v187
	v_mul_f32_e32 v184, v48, v184
	v_mul_f32_e32 v199, v199, v200
	v_mul_f32_e32 v185, v49, v185
	v_mul_f32_e32 v186, v50, v186
	v_cvt_pk_bf16_f32 v192, v196, v197
	v_mul_f32_e32 v187, v51, v187
	v_sub_f32_e32 v188, v194, v100
	v_cvt_pk_bf16_f32 v193, v198, v199
	v_sub_f32_e32 v189, v194, v101
	v_sub_f32_e32 v190, v194, v102
	v_sub_f32_e32 v191, v194, v103
	ds_write_b64 v215, v[192:193] offset:37888
	v_exp_f32_e32 v188, v188
	v_exp_f32_e32 v189, v189
	ds_write_b64 v217, v[164:165] offset:43008
	v_exp_f32_e32 v190, v190
	v_exp_f32_e32 v191, v191
	ds_write_b64 v217, v[166:167] offset:47616
	v_mul_f32_e32 v188, v52, v188
	v_mul_f32_e32 v189, v53, v189
	v_mul_f32_e32 v201, 0x3fb8aa3b, v168
	v_mul_f32_e32 v190, v54, v190
	v_mul_f32_e32 v191, v55, v191
	ds_write_b32 v218, v201 offset:256
	v_cndmask_b32_e64 v188, 0, v188, s[14:15]
	v_cndmask_b32_e64 v189, 0, v189, s[16:17]
	v_mul_f32_e32 v174, 0x3fb8aa3b, v169
	v_cndmask_b32_e64 v190, 0, v190, s[22:23]
	v_cndmask_b32_e64 v191, 0, v191, s[34:35]
	v_exp_f32_e32 v174, v174
	v_cvt_pk_bf16_f32 v128, v184, v185
	v_cvt_pk_bf16_f32 v129, v186, v187
	v_cvt_pk_bf16_f32 v130, v188, v189
	v_cvt_pk_bf16_f32 v131, v190, v191
	s_nop 1
	v_mfma_f32_16x16x32_bf16 v[24:27], v[56:59], v[128:131], v[24:27]
	s_mul_i32 s65, s56, 0x2000
	s_add_u32 s65, s65, 0x304f1000
	s_add_u32 s48, s0, s65
	s_addc_u32 s49, s1, 0
	s_nop 3
	v_fma_f32 v184, s61, v120, v24
	v_fma_f32 v185, s61, v121, v25
	v_fma_f32 v186, s61, v122, v26
	v_fma_f32 v187, s61, v123, v27
	v_mul_f32_e32 v184, v184, v112
	v_mul_f32_e32 v185, v185, v113
	v_mul_f32_e32 v186, v186, v114
	v_mul_f32_e32 v187, v187, v115
	v_cvt_pk_bf16_f32 v170, v184, v185
	v_cvt_pk_bf16_f32 v171, v186, v187
	global_store_dwordx2 v210, v[170:171], s[48:49]
	s_add_u32 s65, s54, 1
	s_sub_u32 s65, s65, s60
	s_lshl_b32 s65, s65, 6
	s_add_u32 s56, s65, s20
	s_waitcnt lgkmcnt(0)
	s_barrier
	s_add_u32 s54, s54, 1
	s_cmp_ge_u32 s54, s39
	s_cbranch_scc1 .Lssd_done
	ds_read_b128 v[28:31], v223 offset:4096
	ds_read_b128 v[48:51], v227 offset:8192
	ds_read_b128 v[32:35], v224 offset:4096
	ds_read_b128 v[52:55], v228 offset:8192
	ds_read_b128 v[40:43], v225 offset:4096
	ds_read_b128 v[56:59], v229 offset:8192
	ds_read_b128 v[44:47], v226 offset:4096
	ds_read_b128 v[60:63], v230 offset:8192
	ds_read_b32 v194, v231 offset:320
	ds_read_b64_tr_b16 v[96:97], v246 offset:16384
	ds_read_b64_tr_b16 v[98:99], v246 offset:20480
	ds_read_b64_tr_b16 v[100:101], v246 offset:24576
	ds_read_b64_tr_b16 v[102:103], v246 offset:28672
	ds_read_b64_tr_b16 v[104:105], v247 offset:16384
	ds_read_b64_tr_b16 v[106:107], v247 offset:20480
	s_waitcnt lgkmcnt(11)
	ds_read_b64_tr_b16 v[108:109], v247 offset:24576
	ds_read_b64_tr_b16 v[110:111], v247 offset:28672
	ds_read_b64_tr_b16 v[112:113], v243 offset:37888
	ds_read_b64_tr_b16 v[114:115], v243 offset:39168
	s_waitcnt lgkmcnt(11)
	ds_read_b64_tr_b16 v[124:125], v243 offset:37920
	ds_read_b64_tr_b16 v[126:127], v243 offset:39200
	ds_read_b64_tr_b16 v[120:121], v243 offset:40448
	ds_read_b64_tr_b16 v[122:123], v243 offset:41728
	s_waitcnt lgkmcnt(11)
	ds_read_b64_tr_b16 v[128:129], v243 offset:40480
	ds_read_b64_tr_b16 v[130:131], v243 offset:41760
	ds_read_b128 v[64:67], v223 offset:16384
	ds_read_b128 v[68:71], v224 offset:16384
	global_load_dwordx4 v[156:159], v204, s[40:41] offset:2048
	s_waitcnt lgkmcnt(11)
	ds_read_b128 v[72:75], v225 offset:16384
	ds_read_b128 v[76:79], v226 offset:16384
	ds_read_b128 v[80:83], v223 offset:20480
	ds_read_b128 v[84:87], v224 offset:20480
	s_waitcnt lgkmcnt(11)
; __device__ __forceinline__ void phase_ssd(const Params& P, int seg, unsigned char* smem) {
;     ...
;             bf16x8 cf[4];
; #pragma unroll
;             for (int k = 0; k < 4; ++k) cf[k] = *(const bf16x8*)(sb + T_CS + (lt * 16 + fr) * 272 + (k * 32 + fq * 8) * 2);
;             f32x4 yo = {0.f, 0.f, 0.f, 0.f};
; #pragma unroll
;             for (int k = 0; k < 4; ++k) { const bf16x8 bb = *(const bf16x8*)((const unsigned char*)StR + (pt * 16 + fr) * 272 + (k * 32 + fq * 8) * 2); yo = mfma16(cf[k], bb, yo); }
; { const f32x4 a4 = *(const f32x4*)(acP + lt * 16 + fq * 4);
; #pragma unroll
;               for (int j = 0; j < 4; ++j) yo[j] *= __expf(a4[j]); }
;             const float acl_fr = acP[lt * 16 + fr]; const int lrow = lt * 16 + fr;
; #pragma unroll
;             for (int t = 0; t < 2; ++t) {
;                 if (2 * t <= lt) {
;                     v2u xb0, xb1;
;                     { const unsigned a0 = lds0 + par * T_BUF + T_XD + (32 * t + 4 * fq + tq) * 80 + (pt * 16 + 4 * tp) * 2, a1 = a0 + 16 * 80; TR_ISSUE(xb0, a0); TR_ISSUE(xb1, a1); }
;                     float m[8];
;                     { f32x4 s0 = {0.f, 0.f, 0.f, 0.f}, s1 = {0.f, 0.f, 0.f, 0.f};
; #pragma unroll
;                       for (int k = 0; k < 4; ++k) { const bf16x8 bf0 = *(const bf16x8*)(sb + T_BS + ((2 * t) * 16 + fr) * 272 + (k * 32 + fq * 8) * 2), bf1 = *(const bf16x8*)(sb + T_BS + ((2 * t + 1) * 16 + fr) * 272 + (k * 32 + fq * 8) * 2);
;                           s0 = mfma16(bf0, cf[k], s0); s1 = mfma16(bf1, cf[k], s1); }
;                       const f32x4 a0 = *(const f32x4*)(acP + (2 * t) * 16 + fq * 4), a1 = *(const f32x4*)(acP + (2 * t + 1) * 16 + fq * 4);
; #pragma unroll
;                       for (int j = 0; j < 4; ++j) { const int si0 = (2 * t) * 16 + fq * 4 + j, si1 = si0 + 16;
;                           const float e0 = s0[j] * __expf(fminf(acl_fr - a0[j], 0.f)), e1 = s1[j] * __expf(fminf(acl_fr - a1[j], 0.f));
;                           m[j] = (si0 <= lrow) ? e0 : 0.f; m[4 + j] = (si1 <= lrow) ? e1 : 0.f; } }
;                     v4u mp; mp.x = cvt_pk_bf16(m[0], m[1]); mp.y = cvt_pk_bf16(m[2], m[3]); mp.z = cvt_pk_bf16(m[4], m[5]); mp.w = cvt_pk_bf16(m[6], m[7]);
;                     asm volatile("s_waitcnt lgkmcnt(0)" : "+v"(xb0), "+v"(xb1) :: "memory");
;                     yo = mfma16(__builtin_bit_cast(bf16x8, mp), mk8(xb0, xb1), yo);
	ds_read_b128 v[88:91], v225 offset:20480
	ds_read_b128 v[92:95], v226 offset:20480
	global_load_dwordx4 v[160:163], v205, s[40:41] offset:2048
	v_mfma_f32_16x16x32_bf16 v[24:27], v[48:51], v[28:31], 0
	v_mfma_f32_16x16x32_bf16 v[188:191], v[52:55], v[32:35], 0
	v_mfma_f32_16x16x32_bf16 v[24:27], v[56:59], v[40:43], v[24:27]
	v_mfma_f32_16x16x32_bf16 v[188:191], v[60:63], v[44:47], v[188:191]
	ds_read_b64_tr_b16 v[56:57], v234 offset:32768
	ds_read_b64_tr_b16 v[58:59], v234 offset:34048
	global_load_dwordx4 v[148:151], v204, s[40:41]
	v_mul_f32_e32 v8, v8, v174
	v_mul_f32_e32 v9, v9, v174
	v_mul_f32_e32 v10, v10, v174
	v_mul_f32_e32 v11, v11, v174
	v_mul_f32_e32 v12, v12, v174
	v_mul_f32_e32 v13, v13, v174
	v_mul_f32_e32 v14, v14, v174
	global_load_dwordx4 v[152:155], v205, s[40:41]
	v_mul_f32_e32 v15, v15, v174
	v_mul_f32_e32 v16, v16, v174
	v_mul_f32_e32 v17, v17, v174
	v_mul_f32_e32 v18, v18, v174
	v_mul_f32_e32 v19, v19, v174
	v_mul_f32_e32 v20, v20, v174
	global_load_dwordx2 v[164:165], v206, s[40:41]
	v_mul_f32_e32 v21, v21, v174
	v_mul_f32_e32 v22, v22, v174
	v_mul_f32_e32 v23, v23, v174
	v_mfma_f32_16x16x32_bf16 v[8:11], v[96:99], v[112:115], v[8:11]
	s_waitcnt lgkmcnt(14)
	v_mfma_f32_16x16x32_bf16 v[12:15], v[96:99], v[124:127], v[12:15]
	v_mfma_f32_16x16x32_bf16 v[16:19], v[104:107], v[112:115], v[16:19]
	v_mfma_f32_16x16x32_bf16 v[20:23], v[104:107], v[124:127], v[20:23]
	global_load_dwordx2 v[166:167], v207, s[42:43] nt
	s_waitcnt lgkmcnt(12)
	v_mfma_f32_16x16x32_bf16 v[8:11], v[100:103], v[120:123], v[8:11]
	s_waitcnt lgkmcnt(10)
	v_mfma_f32_16x16x32_bf16 v[12:15], v[100:103], v[128:131], v[12:15]
	v_mfma_f32_16x16x32_bf16 v[16:19], v[108:111], v[120:123], v[16:19]
	v_mfma_f32_16x16x32_bf16 v[20:23], v[108:111], v[128:131], v[20:23]
	ds_read_b128 v[96:99], v232 offset:256
	ds_read_b128 v[100:103], v232 offset:320
	global_load_dword v118, v208, s[44:45]
	ds_read_b64 v[124:125], v236 offset:44160
	ds_read_b64 v[126:127], v236 offset:48768
	s_waitcnt lgkmcnt(13)
	v_mfma_f32_16x16x32_bf16 v[48:51], v[64:67], v[28:31], 0
	s_waitcnt lgkmcnt(9)
	v_mfma_f32_16x16x32_bf16 v[52:55], v[80:83], v[28:31], 0
	v_mfma_f32_16x16x32_bf16 v[48:51], v[68:71], v[32:35], v[48:51]
	s_waitcnt lgkmcnt(8)
	v_mfma_f32_16x16x32_bf16 v[52:55], v[84:87], v[32:35], v[52:55]
	global_load_dword v168, v208, s[46:47]
	v_mfma_f32_16x16x32_bf16 v[48:51], v[72:75], v[40:43], v[48:51]
	s_waitcnt lgkmcnt(7)
	v_mfma_f32_16x16x32_bf16 v[52:55], v[88:91], v[40:43], v[52:55]
	v_mfma_f32_16x16x32_bf16 v[48:51], v[76:79], v[44:47], v[48:51]
	s_waitcnt lgkmcnt(6)
	v_mfma_f32_16x16x32_bf16 v[52:55], v[92:95], v[44:47], v[52:55]
	v_exp_f32_e32 v195, v194
	v_add_f32_e32 v24, v24, v188
	v_add_f32_e32 v25, v25, v189
	global_load_dword v169, v209, s[46:47]
	v_add_f32_e32 v26, v26, v190
	v_add_f32_e32 v27, v27, v191
	v_mul_f32_e32 v24, v24, v195
	v_mul_f32_e32 v25, v25, v195
	v_mul_f32_e32 v26, v26, v195
	v_mul_f32_e32 v27, v27, v195
	s_add_u32 s66, s54, 3
	s_cmp_lt_u32 s66, s39
	s_cselect_b32 s74, 0xc0000, 0
	s_cselect_b32 s75, 0x280000, 0
	s_cselect_b32 s76, 0x4000, 0
	s_add_u32 s40, s40, s74
	s_addc_u32 s41, s41, 0
	s_add_u32 s42, s42, s75
	s_addc_u32 s43, s43, 0
	s_add_u32 s44, s44, s76
	s_addc_u32 s45, s45, 0
	s_add_u32 s46, s46, s76
	s_addc_u32 s47, s47, 0
	v_cvt_pk_bf16_f32 v184, v8, v9
	v_cvt_pk_bf16_f32 v185, v10, v11
	s_waitcnt vmcnt(10)
	v_cvt_pk_bf16_f32 v186, v12, v13
	v_cvt_pk_bf16_f32 v187, v14, v15
	ds_write_b128 v212, v[140:143]
	v_cvt_pk_bf16_f32 v188, v16, v17
	v_cvt_pk_bf16_f32 v189, v18, v19
	v_cvt_pk_bf16_f32 v190, v20, v21
	ds_write_b128 v212, v[144:147] offset:8192
	v_cvt_pk_bf16_f32 v191, v22, v23
	ds_write_b64 v248, v[184:185]
	ds_write_b128 v212, v[132:135] offset:16384
	ds_write_b64 v248, v[186:187] offset:4096
	ds_write_b64 v249, v[188:189]
	ds_write_b128 v212, v[136:139] offset:24576
	ds_write_b64 v249, v[190:191] offset:4096
	s_waitcnt lgkmcnt(8)
	v_lshlrev_b32_e32 v112, 16, v126
	v_sub_f32_e32 v200, v117, v116
	v_and_b32_e32 v113, 0xffff0000, v126
	v_lshlrev_b32_e32 v114, 16, v127
	v_mul_f32_e32 v200, 0x3fb8aa3b, v200
	v_and_b32_e32 v115, 0xffff0000, v127
	v_mul_f32_e32 v120, 0xbfb8aa3b, v112
	v_exp_f32_e32 v200, v200
	v_mul_f32_e32 v121, 0xbfb8aa3b, v113
	v_mul_f32_e32 v122, 0xbfb8aa3b, v114
	v_lshlrev_b32_e32 v196, 16, v4
	v_mul_f32_e32 v123, 0xbfb8aa3b, v115
	v_exp_f32_e32 v120, v120
	v_and_b32_e32 v197, 0xffff0000, v4
	v_exp_f32_e32 v121, v121
	v_exp_f32_e32 v122, v122
	v_exp_f32_e32 v123, v123
	v_lshlrev_b32_e32 v198, 16, v5
	v_add_f32_e32 v120, 1.0, v120
	v_add_f32_e32 v121, 1.0, v121
	v_and_b32_e32 v199, 0xffff0000, v5
	v_add_f32_e32 v122, 1.0, v122
	v_add_f32_e32 v123, 1.0, v123
	v_mul_f32_e32 v196, v196, v6
	v_rcp_f32_e32 v120, v120
	v_rcp_f32_e32 v121, v121
	v_mul_f32_e32 v197, v197, v6
	v_rcp_f32_e32 v122, v122
	v_rcp_f32_e32 v123, v123
	v_mul_f32_e32 v198, v198, v6
	v_mul_f32_e32 v112, v120, v112
	v_mul_f32_e32 v113, v121, v113
	v_mul_f32_e32 v199, v199, v6
	v_mul_f32_e32 v114, v122, v114
	v_mul_f32_e32 v115, v123, v115
	v_cvt_pk_bf16_f32 v202, v196, v197
	v_lshlrev_b32_e32 v120, 16, v124
	v_and_b32_e32 v121, 0xffff0000, v124
	v_lshlrev_b32_e32 v122, 16, v125
	v_cvt_pk_bf16_f32 v203, v198, v199
	v_and_b32_e32 v123, 0xffff0000, v125
	v_sub_f32_e32 v184, v194, v96
	ds_write_b64 v214, v[202:203] offset:32768
	v_sub_f32_e32 v185, v194, v97
	v_sub_f32_e32 v186, v194, v98
	v_mul_f32_e32 v196, v196, v200
	v_sub_f32_e32 v187, v194, v99
	v_exp_f32_e32 v184, v184
	v_mul_f32_e32 v197, v197, v200
	v_exp_f32_e32 v185, v185
	v_exp_f32_e32 v186, v186
	v_mul_f32_e32 v198, v198, v200
	v_exp_f32_e32 v187, v187
	v_mul_f32_e32 v184, v48, v184
; __device__ __forceinline__ unsigned cvt_pk_bf16(float lo, float hi) { unsigned r; asm volatile("v_cvt_pk_bf16_f32 %0, %1, %2" : "=v"(r) : "v"(lo), "v"(hi)); return r; }
; __device__ __forceinline__ void phase_ssd(const Params& P, int seg, unsigned char* smem) {
;     ...
;             bf16x8 cf[4];
; #pragma unroll
;             for (int k = 0; k < 4; ++k) cf[k] = *(const bf16x8*)(sb + T_CS + (lt * 16 + fr) * 272 + (k * 32 + fq * 8) * 2);
;             f32x4 yo = {0.f, 0.f, 0.f, 0.f};
; #pragma unroll
;             for (int k = 0; k < 4; ++k) { const bf16x8 bb = *(const bf16x8*)((const unsigned char*)StR + (pt * 16 + fr) * 272 + (k * 32 + fq * 8) * 2); yo = mfma16(cf[k], bb, yo); }
; { const f32x4 a4 = *(const f32x4*)(acP + lt * 16 + fq * 4);
; #pragma unroll
;               for (int j = 0; j < 4; ++j) yo[j] *= __expf(a4[j]); }
;             const float acl_fr = acP[lt * 16 + fr]; const int lrow = lt * 16 + fr;
; #pragma unroll
;             for (int t = 0; t < 2; ++t) {
;                 if (2 * t <= lt) {
;                     v2u xb0, xb1;
;                     { const unsigned a0 = lds0 + par * T_BUF + T_XD + (32 * t + 4 * fq + tq) * 80 + (pt * 16 + 4 * tp) * 2, a1 = a0 + 16 * 80; TR_ISSUE(xb0, a0); TR_ISSUE(xb1, a1); }
;                     float m[8];
;                     { f32x4 s0 = {0.f, 0.f, 0.f, 0.f}, s1 = {0.f, 0.f, 0.f, 0.f};
; #pragma unroll
;     ...
;                           const float e0 = s0[j] * __expf(fminf(acl_fr - a0[j], 0.f)), e1 = s1[j] * __expf(fminf(acl_fr - a1[j], 0.f));
;                           m[j] = (si0 <= lrow) ? e0 : 0.f; m[4 + j] = (si1 <= lrow) ? e1 : 0.f; } }
;                     v4u mp; mp.x = cvt_pk_bf16(m[0], m[1]); mp.y = cvt_pk_bf16(m[2], m[3]); mp.z = cvt_pk_bf16(m[4], m[5]); mp.w = cvt_pk_bf16(m[6], m[7]);
;                     asm volatile("s_waitcnt lgkmcnt(0)" : "+v"(xb0), "+v"(xb1) :: "memory");
;                     yo = mfma16(__builtin_bit_cast(bf16x8, mp), mk8(xb0, xb1), yo);
;                 }
;             }
; #pragma unroll
;             for (int j = 0; j < 4; ++j) { const int l = lt * 16 + fq * 4 + j, p = pt * 16 + fr; const float xv = bf2f(*(const bf16*)(sb + T_XS + l * 64 + p * 2)), zv = bf2f(*(const bf16*)(sb + T_ZS + l * 64 + p * 2));
;                 ypre[(size_t)(row0 + l) * DINNER + h * 64 + ph * 32 + p] = f2bfh((yo[j] + Dh * xv) * siluf_(zv)); }
	v_mul_f32_e32 v199, v199, v200
	v_mul_f32_e32 v185, v49, v185
	v_mul_f32_e32 v186, v50, v186
	v_cvt_pk_bf16_f32 v192, v196, v197
	v_mul_f32_e32 v187, v51, v187
	v_sub_f32_e32 v188, v194, v100
	v_cvt_pk_bf16_f32 v193, v198, v199
	v_sub_f32_e32 v189, v194, v101
	v_sub_f32_e32 v190, v194, v102
	v_sub_f32_e32 v191, v194, v103
	ds_write_b64 v214, v[192:193] offset:37888
	v_exp_f32_e32 v188, v188
	v_exp_f32_e32 v189, v189
	ds_write_b64 v216, v[4:5] offset:43008
	v_exp_f32_e32 v190, v190
	v_exp_f32_e32 v191, v191
	ds_write_b64 v216, v[36:37] offset:47616
	v_mul_f32_e32 v188, v52, v188
	v_mul_f32_e32 v189, v53, v189
	v_mul_f32_e32 v201, 0x3fb8aa3b, v116
	v_mul_f32_e32 v190, v54, v190
	v_mul_f32_e32 v191, v55, v191
	ds_write_b32 v218, v201
	v_cndmask_b32_e64 v188, 0, v188, s[14:15]
	v_cndmask_b32_e64 v189, 0, v189, s[16:17]
	v_mul_f32_e32 v174, 0x3fb8aa3b, v117
	v_cndmask_b32_e64 v190, 0, v190, s[22:23]
	v_cndmask_b32_e64 v191, 0, v191, s[34:35]
	v_exp_f32_e32 v174, v174
	v_cvt_pk_bf16_f32 v128, v184, v185
	v_cvt_pk_bf16_f32 v129, v186, v187
	v_cvt_pk_bf16_f32 v130, v188, v189
	v_cvt_pk_bf16_f32 v131, v190, v191
	s_nop 1
	v_mfma_f32_16x16x32_bf16 v[24:27], v[56:59], v[128:131], v[24:27]
	s_mul_i32 s65, s56, 0x2000
	s_add_u32 s65, s65, 0x304f1000
	s_add_u32 s48, s0, s65
	s_addc_u32 s49, s1, 0
	s_nop 3
	v_fma_f32 v184, s61, v120, v24
	v_fma_f32 v185, s61, v121, v25
	v_fma_f32 v186, s61, v122, v26
	v_fma_f32 v187, s61, v123, v27
	v_mul_f32_e32 v184, v184, v112
	v_mul_f32_e32 v185, v185, v113
	v_mul_f32_e32 v186, v186, v114
	v_mul_f32_e32 v187, v187, v115
	v_cvt_pk_bf16_f32 v170, v184, v185
	v_cvt_pk_bf16_f32 v171, v186, v187
	global_store_dwordx2 v210, v[170:171], s[48:49]
	s_add_u32 s65, s54, 1
	s_sub_u32 s65, s65, s60
	s_lshl_b32 s65, s65, 6
	s_add_u32 s56, s65, s20
	s_waitcnt lgkmcnt(0)
	s_barrier
	s_add_u32 s54, s54, 1
	s_cmp_lt_u32 s54, s39
	s_cbranch_scc1 .Lssd_loop1
	s_branch .Lssd_done
.Lssd_loop2:
	ds_read_b128 v[28:31], v219 offset:8192
	ds_read_b128 v[48:51], v227
	ds_read_b128 v[32:35], v220 offset:8192
	ds_read_b128 v[52:55], v228
	ds_read_b128 v[40:43], v221 offset:8192
	ds_read_b128 v[56:59], v229
	ds_read_b128 v[44:47], v222 offset:8192
	ds_read_b128 v[60:63], v230
	ds_read_b32 v194, v231 offset:128
	ds_read_b128 v[64:67], v219 offset:16384
	ds_read_b128 v[68:71], v220 offset:16384
	ds_read_b128 v[72:75], v221 offset:16384
	ds_read_b128 v[76:79], v222 offset:16384
	ds_read_b128 v[80:83], v219 offset:20480
	ds_read_b128 v[84:87], v220 offset:20480
	global_load_dwordx4 v[140:143], v204, s[40:41] offset:2048
	s_waitcnt lgkmcnt(11)
	ds_read_b128 v[88:91], v221 offset:20480
	ds_read_b128 v[92:95], v222 offset:20480
	ds_read_b128 v[96:99], v232
	ds_read_b128 v[100:103], v232 offset:64
	s_waitcnt lgkmcnt(11)
	ds_read_b64 v[124:125], v235 offset:45312
	global_load_dwordx4 v[144:147], v205, s[40:41] offset:2048
	ds_read_b64 v[126:127], v235 offset:49920
	v_mfma_f32_16x16x32_bf16 v[24:27], v[48:51], v[28:31], 0
	v_mfma_f32_16x16x32_bf16 v[188:191], v[52:55], v[32:35], 0
	v_mfma_f32_16x16x32_bf16 v[24:27], v[56:59], v[40:43], v[24:27]
	v_mfma_f32_16x16x32_bf16 v[188:191], v[60:63], v[44:47], v[188:191]
	ds_read_b64_tr_b16 v[56:57], v233 offset:32768
	global_load_dwordx4 v[132:135], v204, s[40:41]
	ds_read_b64_tr_b16 v[58:59], v233 offset:34048
	s_waitcnt lgkmcnt(13)
	v_mfma_f32_16x16x32_bf16 v[48:51], v[64:67], v[28:31], 0
	s_waitcnt lgkmcnt(9)
	v_mfma_f32_16x16x32_bf16 v[52:55], v[80:83], v[28:31], 0
	v_mfma_f32_16x16x32_bf16 v[48:51], v[68:71], v[32:35], v[48:51]
	s_waitcnt lgkmcnt(8)
	v_mfma_f32_16x16x32_bf16 v[52:55], v[84:87], v[32:35], v[52:55]
	v_mfma_f32_16x16x32_bf16 v[48:51], v[72:75], v[40:43], v[48:51]
	global_load_dwordx4 v[136:139], v205, s[40:41]
	s_waitcnt lgkmcnt(7)
	v_mfma_f32_16x16x32_bf16 v[52:55], v[88:91], v[40:43], v[52:55]
	v_mfma_f32_16x16x32_bf16 v[48:51], v[76:79], v[44:47], v[48:51]
	s_waitcnt lgkmcnt(6)
	v_mfma_f32_16x16x32_bf16 v[52:55], v[92:95], v[44:47], v[52:55]
	ds_read_b128 v[64:67], v219 offset:24576
	ds_read_b128 v[68:71], v220 offset:24576
	ds_read_b128 v[72:75], v221 offset:24576
	global_load_dwordx2 v[4:5], v206, s[40:41]
	ds_read_b128 v[76:79], v222 offset:24576
	ds_read_b64_tr_b16 v[60:61], v233 offset:35328
	ds_read_b64_tr_b16 v[62:63], v233 offset:36608
	v_exp_f32_e32 v195, v194
	v_add_f32_e32 v24, v24, v188
	v_add_f32_e32 v25, v25, v189
	global_load_dwordx2 v[36:37], v207, s[42:43] nt
	v_add_f32_e32 v26, v26, v190
	v_add_f32_e32 v27, v27, v191
	v_mul_f32_e32 v24, v24, v195
	v_mul_f32_e32 v25, v25, v195
	v_mul_f32_e32 v26, v26, v195
	global_load_dword v6, v208, s[44:45]
	v_mul_f32_e32 v27, v27, v195
	s_waitcnt lgkmcnt(8)
	v_lshlrev_b32_e32 v112, 16, v126
	v_and_b32_e32 v113, 0xffff0000, v126
	v_lshlrev_b32_e32 v114, 16, v127
	v_and_b32_e32 v115, 0xffff0000, v127
	v_mul_f32_e32 v120, 0xbfb8aa3b, v112
	global_load_dword v116, v208, s[46:47]
	v_mul_f32_e32 v121, 0xbfb8aa3b, v113
	v_mul_f32_e32 v122, 0xbfb8aa3b, v114
	v_mul_f32_e32 v123, 0xbfb8aa3b, v115
	v_exp_f32_e32 v120, v120
	v_exp_f32_e32 v121, v121
	v_exp_f32_e32 v122, v122
	global_load_dword v117, v209, s[46:47]
	v_exp_f32_e32 v123, v123
	v_add_f32_e32 v120, 1.0, v120
	v_add_f32_e32 v121, 1.0, v121
	v_add_f32_e32 v122, 1.0, v122
	v_add_f32_e32 v123, 1.0, v123
	v_rcp_f32_e32 v120, v120
	s_add_u32 s66, s54, 3
	s_cmp_lt_u32 s66, s39
	s_cselect_b32 s74, 0xc0000, 0
	s_cselect_b32 s75, 0x280000, 0
	s_cselect_b32 s76, 0x4000, 0
	s_add_u32 s40, s40, s74
	s_addc_u32 s41, s41, 0
	s_add_u32 s42, s42, s75
	s_addc_u32 s43, s43, 0
	s_add_u32 s44, s44, s76
	s_addc_u32 s45, s45, 0
	s_add_u32 s46, s46, s76
	s_addc_u32 s47, s47, 0
	v_rcp_f32_e32 v121, v121
	v_rcp_f32_e32 v122, v122
	s_waitcnt vmcnt(10)
; __device__ __forceinline__ unsigned cvt_pk_bf16(float lo, float hi) { unsigned r; asm volatile("v_cvt_pk_bf16_f32 %0, %1, %2" : "=v"(r) : "v"(lo), "v"(hi)); return r; }
; __device__ __forceinline__ void phase_ssd(const Params& P, int seg, unsigned char* smem) {
;     ...
;             { const float e2 = __expf(R.alast - R.acl);
; #pragma unroll
;               for (int i = 0; i < 2; ++i) { const int q = tid + 512 * i, l = q >> 4, c8 = q & 15; *(v4u*)(sb + T_CS + l * 272 + c8 * 16) = R.Cr[i]; *(v4u*)(sb + T_BS + l * 272 + c8 * 16) = R.Br[i]; }
;               const int l = tid >> 3, p4 = (tid & 7) * 4;
;               const float x0 = bflo(R.Xr.x) * R.dtl, x1 = bfhi(R.Xr.x) * R.dtl, x2 = bflo(R.Xr.y) * R.dtl, x3 = bfhi(R.Xr.y) * R.dtl;
;               v2u d; d.x = cvt_pk_bf16(x0, x1); d.y = cvt_pk_bf16(x2, x3); *(v2u*)(sb + T_XD + l * 80 + p4 * 2) = d;
;               v2u e; e.x = cvt_pk_bf16(x0 * e2, x1 * e2); e.y = cvt_pk_bf16(x2 * e2, x3 * e2); *(v2u*)(sb + T_XE + l * 80 + p4 * 2) = e;
;               *(v2u*)(sb + T_XS + l * 64 + p4 * 2) = R.Xr; *(v2u*)(sb + T_ZS + l * 64 + p4 * 2) = R.Zr;
;               if (w == 0) acP[lane] = R.aclane; }
;             BAR_LDS();
;             if (ci + 2 < nchunks) load_chunk(ci + 2, R);
;             bf16x8 cf[4];
; #pragma unroll
;             for (int k = 0; k < 4; ++k) cf[k] = *(const bf16x8*)(sb + T_CS + (lt * 16 + fr) * 272 + (k * 32 + fq * 8) * 2);
;             f32x4 yo = {0.f, 0.f, 0.f, 0.f};
; #pragma unroll
;             for (int k = 0; k < 4; ++k) { const bf16x8 bb = *(const bf16x8*)((const unsigned char*)StR + (pt * 16 + fr) * 272 + (k * 32 + fq * 8) * 2); yo = mfma16(cf[k], bb, yo); }
; { const f32x4 a4 = *(const f32x4*)(acP + lt * 16 + fq * 4);
; #pragma unroll
;               for (int j = 0; j < 4; ++j) yo[j] *= __expf(a4[j]); }
;             const float acl_fr = acP[lt * 16 + fr]; const int lrow = lt * 16 + fr;
; #pragma unroll
;             for (int t = 0; t < 2; ++t) {
;                 if (2 * t <= lt) {
;                     v2u xb0, xb1;
;                     { const unsigned a0 = lds0 + par * T_BUF + T_XD + (32 * t + 4 * fq + tq) * 80 + (pt * 16 + 4 * tp) * 2, a1 = a0 + 16 * 80; TR_ISSUE(xb0, a0); TR_ISSUE(xb1, a1); }
;                     float m[8];
;                     { f32x4 s0 = {0.f, 0.f, 0.f, 0.f}, s1 = {0.f, 0.f, 0.f, 0.f};
; #pragma unroll
	v_rcp_f32_e32 v123, v123
	v_mul_f32_e32 v112, v120, v112
	ds_write_b128 v213, v[156:159]
	v_mul_f32_e32 v113, v121, v113
	v_mul_f32_e32 v114, v122, v114
	ds_write_b128 v213, v[160:163] offset:8192
	v_mul_f32_e32 v115, v123, v115
	ds_write_b128 v213, v[148:151] offset:16384
	v_lshlrev_b32_e32 v120, 16, v124
	v_and_b32_e32 v121, 0xffff0000, v124
	ds_write_b128 v213, v[152:155] offset:24576
	v_lshlrev_b32_e32 v122, 16, v125
	v_and_b32_e32 v123, 0xffff0000, v125
	v_sub_f32_e32 v200, v169, v168
	v_sub_f32_e32 v184, v194, v96
	v_sub_f32_e32 v185, v194, v97
	v_mul_f32_e32 v200, 0x3fb8aa3b, v200
	v_sub_f32_e32 v186, v194, v98
	v_sub_f32_e32 v187, v194, v99
	v_exp_f32_e32 v200, v200
	v_exp_f32_e32 v184, v184
	v_exp_f32_e32 v185, v185
	v_lshlrev_b32_e32 v196, 16, v164
	v_exp_f32_e32 v186, v186
	v_exp_f32_e32 v187, v187
	v_and_b32_e32 v197, 0xffff0000, v164
	v_mul_f32_e32 v184, v48, v184
	v_mul_f32_e32 v185, v49, v185
	v_lshlrev_b32_e32 v198, 16, v165
	v_mul_f32_e32 v186, v50, v186
	v_mul_f32_e32 v187, v51, v187
	v_and_b32_e32 v199, 0xffff0000, v165
	v_sub_f32_e32 v188, v194, v100
	v_sub_f32_e32 v189, v194, v101
	v_mul_f32_e32 v196, v196, v118
	v_sub_f32_e32 v190, v194, v102
	v_sub_f32_e32 v191, v194, v103
	v_mul_f32_e32 v197, v197, v118
	v_exp_f32_e32 v188, v188
	v_exp_f32_e32 v189, v189
	v_mul_f32_e32 v198, v198, v118
	v_exp_f32_e32 v190, v190
	v_exp_f32_e32 v191, v191
	v_mul_f32_e32 v199, v199, v118
	v_mul_f32_e32 v188, v52, v188
	v_mul_f32_e32 v189, v53, v189
	v_cvt_pk_bf16_f32 v202, v196, v197
	v_mul_f32_e32 v190, v54, v190
	v_mul_f32_e32 v191, v55, v191
	v_cvt_pk_bf16_f32 v203, v198, v199
	v_cvt_pk_bf16_f32 v128, v184, v185
	ds_write_b64 v215, v[202:203] offset:32768
	v_cvt_pk_bf16_f32 v129, v186, v187
	v_cvt_pk_bf16_f32 v130, v188, v189
	v_mul_f32_e32 v196, v196, v200
	v_cvt_pk_bf16_f32 v131, v190, v191
	s_waitcnt lgkmcnt(11)
	s_nop 0
	v_mfma_f32_16x16x32_bf16 v[24:27], v[56:59], v[128:131], v[24:27]
	v_mul_f32_e32 v197, v197, v200
	ds_read_b128 v[96:99], v232 offset:128
	s_waitcnt lgkmcnt(11)
	v_mfma_f32_16x16x32_bf16 v[48:51], v[64:67], v[28:31], 0
	v_mul_f32_e32 v198, v198, v200
	s_waitcnt lgkmcnt(10)
	v_mfma_f32_16x16x32_bf16 v[48:51], v[68:71], v[32:35], v[48:51]
	s_waitcnt lgkmcnt(9)
	v_mfma_f32_16x16x32_bf16 v[48:51], v[72:75], v[40:43], v[48:51]
	v_mul_f32_e32 v199, v199, v200
	s_waitcnt lgkmcnt(8)
	v_mfma_f32_16x16x32_bf16 v[48:51], v[76:79], v[44:47], v[48:51]
	s_waitcnt lgkmcnt(0)
	v_sub_f32_e32 v184, v194, v96
	v_cvt_pk_bf16_f32 v192, v196, v197
	v_sub_f32_e32 v185, v194, v97
	v_sub_f32_e32 v186, v194, v98
	v_cvt_pk_bf16_f32 v193, v198, v199
	v_sub_f32_e32 v187, v194, v99
	v_exp_f32_e32 v184, v184
	ds_write_b64 v215, v[192:193] offset:37888
	v_exp_f32_e32 v185, v185
	v_exp_f32_e32 v186, v186
	ds_write_b64 v217, v[164:165] offset:43008
	v_exp_f32_e32 v187, v187
	v_mul_f32_e32 v184, v48, v184
	ds_write_b64 v217, v[166:167] offset:47616
	v_mul_f32_e32 v185, v49, v185
	v_mul_f32_e32 v186, v50, v186
	v_mul_f32_e32 v201, 0x3fb8aa3b, v168
	v_mul_f32_e32 v187, v51, v187
	v_cndmask_b32_e64 v184, 0, v184, s[14:15]
	ds_write_b32 v218, v201 offset:256
	v_cndmask_b32_e64 v185, 0, v185, s[16:17]
	v_cndmask_b32_e64 v186, 0, v186, s[22:23]
	v_mul_f32_e32 v174, 0x3fb8aa3b, v169
	v_cndmask_b32_e64 v187, 0, v187, s[34:35]
	v_cvt_pk_bf16_f32 v128, v184, v185
	v_exp_f32_e32 v174, v174
	v_cvt_pk_bf16_f32 v129, v186, v187
	v_mov_b32_e32 v130, 0
	v_mov_b32_e32 v131, 0
	s_nop 1
	v_mfma_f32_16x16x32_bf16 v[24:27], v[60:63], v[128:131], v[24:27]
	s_mul_i32 s65, s56, 0x2000
	s_add_u32 s65, s65, 0x304f1000
	s_add_u32 s48, s0, s65
	s_addc_u32 s49, s1, 0
	s_nop 3
	v_fma_f32 v184, s61, v120, v24
	v_fma_f32 v185, s61, v121, v25
	v_fma_f32 v186, s61, v122, v26
	v_fma_f32 v187, s61, v123, v27
	v_mul_f32_e32 v184, v184, v112
	v_mul_f32_e32 v185, v185, v113
	v_mul_f32_e32 v186, v186, v114
	v_mul_f32_e32 v187, v187, v115
	v_cvt_pk_bf16_f32 v170, v184, v185
	v_cvt_pk_bf16_f32 v171, v186, v187
	global_store_dwordx2 v210, v[170:171], s[48:49]
	s_add_u32 s65, s54, 1
	s_sub_u32 s65, s65, s60
	s_lshl_b32 s65, s65, 6
	s_add_u32 s56, s65, s20
	s_waitcnt lgkmcnt(0)
	s_barrier
	s_add_u32 s54, s54, 1
	s_cmp_ge_u32 s54, s39
	s_cbranch_scc1 .Lssd_done
	ds_read_b128 v[28:31], v223 offset:8192
	ds_read_b128 v[48:51], v227 offset:8192
	ds_read_b128 v[32:35], v224 offset:8192
	ds_read_b128 v[52:55], v228 offset:8192
	ds_read_b128 v[40:43], v225 offset:8192
	ds_read_b128 v[56:59], v229 offset:8192
	ds_read_b128 v[44:47], v226 offset:8192
	ds_read_b128 v[60:63], v230 offset:8192
	ds_read_b32 v194, v231 offset:384
	ds_read_b128 v[64:67], v223 offset:16384
	ds_read_b128 v[68:71], v224 offset:16384
	ds_read_b128 v[72:75], v225 offset:16384
	ds_read_b128 v[76:79], v226 offset:16384
	ds_read_b128 v[80:83], v223 offset:20480
	ds_read_b128 v[84:87], v224 offset:20480
	global_load_dwordx4 v[156:159], v204, s[40:41] offset:2048
	s_waitcnt lgkmcnt(11)
	ds_read_b128 v[88:91], v225 offset:20480
	ds_read_b128 v[92:95], v226 offset:20480
	ds_read_b128 v[96:99], v232 offset:256
	ds_read_b128 v[100:103], v232 offset:320
	s_waitcnt lgkmcnt(11)
	ds_read_b64 v[124:125], v236 offset:45312
	global_load_dwordx4 v[160:163], v205, s[40:41] offset:2048
	ds_read_b64 v[126:127], v236 offset:49920
	v_mfma_f32_16x16x32_bf16 v[24:27], v[48:51], v[28:31], 0
	v_mfma_f32_16x16x32_bf16 v[188:191], v[52:55], v[32:35], 0
	v_mfma_f32_16x16x32_bf16 v[24:27], v[56:59], v[40:43], v[24:27]
	v_mfma_f32_16x16x32_bf16 v[188:191], v[60:63], v[44:47], v[188:191]
	ds_read_b64_tr_b16 v[56:57], v234 offset:32768
	global_load_dwordx4 v[148:151], v204, s[40:41]
	ds_read_b64_tr_b16 v[58:59], v234 offset:34048
	s_waitcnt lgkmcnt(13)
; __device__ __forceinline__ unsigned cvt_pk_bf16(float lo, float hi) { unsigned r; asm volatile("v_cvt_pk_bf16_f32 %0, %1, %2" : "=v"(r) : "v"(lo), "v"(hi)); return r; }
; __device__ __forceinline__ void phase_ssd(const Params& P, int seg, unsigned char* smem) {
;     ...
;             { const float e2 = __expf(R.alast - R.acl);
; #pragma unroll
;               for (int i = 0; i < 2; ++i) { const int q = tid + 512 * i, l = q >> 4, c8 = q & 15; *(v4u*)(sb + T_CS + l * 272 + c8 * 16) = R.Cr[i]; *(v4u*)(sb + T_BS + l * 272 + c8 * 16) = R.Br[i]; }
;               const int l = tid >> 3, p4 = (tid & 7) * 4;
;               const float x0 = bflo(R.Xr.x) * R.dtl, x1 = bfhi(R.Xr.x) * R.dtl, x2 = bflo(R.Xr.y) * R.dtl, x3 = bfhi(R.Xr.y) * R.dtl;
;               v2u d; d.x = cvt_pk_bf16(x0, x1); d.y = cvt_pk_bf16(x2, x3); *(v2u*)(sb + T_XD + l * 80 + p4 * 2) = d;
;               v2u e; e.x = cvt_pk_bf16(x0 * e2, x1 * e2); e.y = cvt_pk_bf16(x2 * e2, x3 * e2); *(v2u*)(sb + T_XE + l * 80 + p4 * 2) = e;
;               *(v2u*)(sb + T_XS + l * 64 + p4 * 2) = R.Xr; *(v2u*)(sb + T_ZS + l * 64 + p4 * 2) = R.Zr;
;               if (w == 0) acP[lane] = R.aclane; }
;             BAR_LDS();
;             if (ci + 2 < nchunks) load_chunk(ci + 2, R);
;             bf16x8 cf[4];
; #pragma unroll
;             for (int k = 0; k < 4; ++k) cf[k] = *(const bf16x8*)(sb + T_CS + (lt * 16 + fr) * 272 + (k * 32 + fq * 8) * 2);
;             f32x4 yo = {0.f, 0.f, 0.f, 0.f};
; #pragma unroll
;             for (int k = 0; k < 4; ++k) { const bf16x8 bb = *(const bf16x8*)((const unsigned char*)StR + (pt * 16 + fr) * 272 + (k * 32 + fq * 8) * 2); yo = mfma16(cf[k], bb, yo); }
; { const f32x4 a4 = *(const f32x4*)(acP + lt * 16 + fq * 4);
; #pragma unroll
;               for (int j = 0; j < 4; ++j) yo[j] *= __expf(a4[j]); }
;             const float acl_fr = acP[lt * 16 + fr]; const int lrow = lt * 16 + fr;
; #pragma unroll
;             for (int t = 0; t < 2; ++t) {
;                 if (2 * t <= lt) {
;                     v2u xb0, xb1;
;                     { const unsigned a0 = lds0 + par * T_BUF + T_XD + (32 * t + 4 * fq + tq) * 80 + (pt * 16 + 4 * tp) * 2, a1 = a0 + 16 * 80; TR_ISSUE(xb0, a0); TR_ISSUE(xb1, a1); }
;                     float m[8];
;                     { f32x4 s0 = {0.f, 0.f, 0.f, 0.f}, s1 = {0.f, 0.f, 0.f, 0.f};
; #pragma unroll
	v_mfma_f32_16x16x32_bf16 v[48:51], v[64:67], v[28:31], 0
	s_waitcnt lgkmcnt(9)
	v_mfma_f32_16x16x32_bf16 v[52:55], v[80:83], v[28:31], 0
	v_mfma_f32_16x16x32_bf16 v[48:51], v[68:71], v[32:35], v[48:51]
	s_waitcnt lgkmcnt(8)
	v_mfma_f32_16x16x32_bf16 v[52:55], v[84:87], v[32:35], v[52:55]
	v_mfma_f32_16x16x32_bf16 v[48:51], v[72:75], v[40:43], v[48:51]
	global_load_dwordx4 v[152:155], v205, s[40:41]
	s_waitcnt lgkmcnt(7)
	v_mfma_f32_16x16x32_bf16 v[52:55], v[88:91], v[40:43], v[52:55]
	v_mfma_f32_16x16x32_bf16 v[48:51], v[76:79], v[44:47], v[48:51]
	s_waitcnt lgkmcnt(6)
	v_mfma_f32_16x16x32_bf16 v[52:55], v[92:95], v[44:47], v[52:55]
	ds_read_b128 v[64:67], v223 offset:24576
	ds_read_b128 v[68:71], v224 offset:24576
	ds_read_b128 v[72:75], v225 offset:24576
	global_load_dwordx2 v[164:165], v206, s[40:41]
	ds_read_b128 v[76:79], v226 offset:24576
	ds_read_b64_tr_b16 v[60:61], v234 offset:35328
	ds_read_b64_tr_b16 v[62:63], v234 offset:36608
	v_exp_f32_e32 v195, v194
	v_add_f32_e32 v24, v24, v188
	v_add_f32_e32 v25, v25, v189
	global_load_dwordx2 v[166:167], v207, s[42:43] nt
	v_add_f32_e32 v26, v26, v190
	v_add_f32_e32 v27, v27, v191
	v_mul_f32_e32 v24, v24, v195
	v_mul_f32_e32 v25, v25, v195
	v_mul_f32_e32 v26, v26, v195
	global_load_dword v118, v208, s[44:45]
	v_mul_f32_e32 v27, v27, v195
	s_waitcnt lgkmcnt(8)
	v_lshlrev_b32_e32 v112, 16, v126
	v_and_b32_e32 v113, 0xffff0000, v126
	v_lshlrev_b32_e32 v114, 16, v127
	v_and_b32_e32 v115, 0xffff0000, v127
	v_mul_f32_e32 v120, 0xbfb8aa3b, v112
	global_load_dword v168, v208, s[46:47]
	v_mul_f32_e32 v121, 0xbfb8aa3b, v113
	v_mul_f32_e32 v122, 0xbfb8aa3b, v114
	v_mul_f32_e32 v123, 0xbfb8aa3b, v115
	v_exp_f32_e32 v120, v120
	v_exp_f32_e32 v121, v121
	v_exp_f32_e32 v122, v122
	global_load_dword v169, v209, s[46:47]
	v_exp_f32_e32 v123, v123
	v_add_f32_e32 v120, 1.0, v120
	v_add_f32_e32 v121, 1.0, v121
	v_add_f32_e32 v122, 1.0, v122
	v_add_f32_e32 v123, 1.0, v123
	v_rcp_f32_e32 v120, v120
	s_add_u32 s66, s54, 3
	s_cmp_lt_u32 s66, s39
	s_cselect_b32 s74, 0xc0000, 0
	s_cselect_b32 s75, 0x280000, 0
	s_cselect_b32 s76, 0x4000, 0
	s_add_u32 s40, s40, s74
	s_addc_u32 s41, s41, 0
	s_add_u32 s42, s42, s75
	s_addc_u32 s43, s43, 0
	s_add_u32 s44, s44, s76
	s_addc_u32 s45, s45, 0
	s_add_u32 s46, s46, s76
	s_addc_u32 s47, s47, 0
	v_rcp_f32_e32 v121, v121
	v_rcp_f32_e32 v122, v122
	s_waitcnt vmcnt(10)
	v_rcp_f32_e32 v123, v123
	v_mul_f32_e32 v112, v120, v112
	ds_write_b128 v212, v[140:143]
	v_mul_f32_e32 v113, v121, v113
	v_mul_f32_e32 v114, v122, v114
	ds_write_b128 v212, v[144:147] offset:8192
	v_mul_f32_e32 v115, v123, v115
	ds_write_b128 v212, v[132:135] offset:16384
	v_lshlrev_b32_e32 v120, 16, v124
	v_and_b32_e32 v121, 0xffff0000, v124
	ds_write_b128 v212, v[136:139] offset:24576
	v_lshlrev_b32_e32 v122, 16, v125
	v_and_b32_e32 v123, 0xffff0000, v125
	v_sub_f32_e32 v200, v117, v116
	v_sub_f32_e32 v184, v194, v96
	v_sub_f32_e32 v185, v194, v97
	v_mul_f32_e32 v200, 0x3fb8aa3b, v200
	v_sub_f32_e32 v186, v194, v98
	v_sub_f32_e32 v187, v194, v99
	v_exp_f32_e32 v200, v200
	v_exp_f32_e32 v184, v184
	v_exp_f32_e32 v185, v185
	v_lshlrev_b32_e32 v196, 16, v4
	v_exp_f32_e32 v186, v186
	v_exp_f32_e32 v187, v187
	v_and_b32_e32 v197, 0xffff0000, v4
	v_mul_f32_e32 v184, v48, v184
	v_mul_f32_e32 v185, v49, v185
	v_lshlrev_b32_e32 v198, 16, v5
	v_mul_f32_e32 v186, v50, v186
	v_mul_f32_e32 v187, v51, v187
	v_and_b32_e32 v199, 0xffff0000, v5
	v_sub_f32_e32 v188, v194, v100
	v_sub_f32_e32 v189, v194, v101
	v_mul_f32_e32 v196, v196, v6
	v_sub_f32_e32 v190, v194, v102
	v_sub_f32_e32 v191, v194, v103
	v_mul_f32_e32 v197, v197, v6
	v_exp_f32_e32 v188, v188
	v_exp_f32_e32 v189, v189
	v_mul_f32_e32 v198, v198, v6
	v_exp_f32_e32 v190, v190
	v_exp_f32_e32 v191, v191
	v_mul_f32_e32 v199, v199, v6
	v_mul_f32_e32 v188, v52, v188
	v_mul_f32_e32 v189, v53, v189
	v_cvt_pk_bf16_f32 v202, v196, v197
	v_mul_f32_e32 v190, v54, v190
	v_mul_f32_e32 v191, v55, v191
	v_cvt_pk_bf16_f32 v203, v198, v199
	v_cvt_pk_bf16_f32 v128, v184, v185
	ds_write_b64 v214, v[202:203] offset:32768
	v_cvt_pk_bf16_f32 v129, v186, v187
	v_cvt_pk_bf16_f32 v130, v188, v189
	v_mul_f32_e32 v196, v196, v200
	v_cvt_pk_bf16_f32 v131, v190, v191
	s_waitcnt lgkmcnt(11)
	s_nop 0
	v_mfma_f32_16x16x32_bf16 v[24:27], v[56:59], v[128:131], v[24:27]
	v_mul_f32_e32 v197, v197, v200
	ds_read_b128 v[96:99], v232 offset:384
	s_waitcnt lgkmcnt(11)
	v_mfma_f32_16x16x32_bf16 v[48:51], v[64:67], v[28:31], 0
	v_mul_f32_e32 v198, v198, v200
	s_waitcnt lgkmcnt(10)
	v_mfma_f32_16x16x32_bf16 v[48:51], v[68:71], v[32:35], v[48:51]
	s_waitcnt lgkmcnt(9)
	v_mfma_f32_16x16x32_bf16 v[48:51], v[72:75], v[40:43], v[48:51]
	v_mul_f32_e32 v199, v199, v200
	s_waitcnt lgkmcnt(8)
	v_mfma_f32_16x16x32_bf16 v[48:51], v[76:79], v[44:47], v[48:51]
	s_waitcnt lgkmcnt(0)
	v_sub_f32_e32 v184, v194, v96
	v_cvt_pk_bf16_f32 v192, v196, v197
	v_sub_f32_e32 v185, v194, v97
	v_sub_f32_e32 v186, v194, v98
	v_cvt_pk_bf16_f32 v193, v198, v199
	v_sub_f32_e32 v187, v194, v99
	v_exp_f32_e32 v184, v184
	ds_write_b64 v214, v[192:193] offset:37888
	v_exp_f32_e32 v185, v185
	v_exp_f32_e32 v186, v186
	ds_write_b64 v216, v[4:5] offset:43008
	v_exp_f32_e32 v187, v187
	v_mul_f32_e32 v184, v48, v184
	ds_write_b64 v216, v[36:37] offset:47616
	v_mul_f32_e32 v185, v49, v185
	v_mul_f32_e32 v186, v50, v186
	v_mul_f32_e32 v201, 0x3fb8aa3b, v116
	v_mul_f32_e32 v187, v51, v187
	v_cndmask_b32_e64 v184, 0, v184, s[14:15]
	ds_write_b32 v218, v201
	v_cndmask_b32_e64 v185, 0, v185, s[16:17]
	v_cndmask_b32_e64 v186, 0, v186, s[22:23]
	v_mul_f32_e32 v174, 0x3fb8aa3b, v117
	v_cndmask_b32_e64 v187, 0, v187, s[34:35]
	v_cvt_pk_bf16_f32 v128, v184, v185
	v_exp_f32_e32 v174, v174
	v_cvt_pk_bf16_f32 v129, v186, v187
	v_mov_b32_e32 v130, 0
	v_mov_b32_e32 v131, 0
	s_nop 1
	v_mfma_f32_16x16x32_bf16 v[24:27], v[60:63], v[128:131], v[24:27]
	s_mul_i32 s65, s56, 0x2000
	s_add_u32 s65, s65, 0x304f1000
	s_add_u32 s48, s0, s65
	s_addc_u32 s49, s1, 0
	s_nop 3
	v_fma_f32 v184, s61, v120, v24
	v_fma_f32 v185, s61, v121, v25
	v_fma_f32 v186, s61, v122, v26
	v_fma_f32 v187, s61, v123, v27
	v_mul_f32_e32 v184, v184, v112
	v_mul_f32_e32 v185, v185, v113
	v_mul_f32_e32 v186, v186, v114
	v_mul_f32_e32 v187, v187, v115
	v_cvt_pk_bf16_f32 v170, v184, v185
	v_cvt_pk_bf16_f32 v171, v186, v187
	global_store_dwordx2 v210, v[170:171], s[48:49]
	s_add_u32 s65, s54, 1
	s_sub_u32 s65, s65, s60
	s_lshl_b32 s65, s65, 6
	s_add_u32 s56, s65, s20
	s_waitcnt lgkmcnt(0)
	s_barrier
	s_add_u32 s54, s54, 1
	s_cmp_lt_u32 s54, s39
	s_cbranch_scc1 .Lssd_loop2
	s_branch .Lssd_done
; __device__ __forceinline__ void phase_ssd(const Params& P, int seg, unsigned char* smem) {
;     ...
;             bf16x8 cf[4];
; #pragma unroll
;             for (int k = 0; k < 4; ++k) cf[k] = *(const bf16x8*)(sb + T_CS + (lt * 16 + fr) * 272 + (k * 32 + fq * 8) * 2);
;             f32x4 yo = {0.f, 0.f, 0.f, 0.f};
; #pragma unroll
;             for (int k = 0; k < 4; ++k) { const bf16x8 bb = *(const bf16x8*)((const unsigned char*)StR + (pt * 16 + fr) * 272 + (k * 32 + fq * 8) * 2); yo = mfma16(cf[k], bb, yo); }
; { const f32x4 a4 = *(const f32x4*)(acP + lt * 16 + fq * 4);
; #pragma unroll
;               for (int j = 0; j < 4; ++j) yo[j] *= __expf(a4[j]); }
;             const float acl_fr = acP[lt * 16 + fr]; const int lrow = lt * 16 + fr;
; #pragma unroll
;             for (int t = 0; t < 2; ++t) {
;                 if (2 * t <= lt) {
;                     v2u xb0, xb1;
;                     { const unsigned a0 = lds0 + par * T_BUF + T_XD + (32 * t + 4 * fq + tq) * 80 + (pt * 16 + 4 * tp) * 2, a1 = a0 + 16 * 80; TR_ISSUE(xb0, a0); TR_ISSUE(xb1, a1); }
;                     float m[8];
;                     { f32x4 s0 = {0.f, 0.f, 0.f, 0.f}, s1 = {0.f, 0.f, 0.f, 0.f};
; #pragma unroll
;                       for (int k = 0; k < 4; ++k) { const bf16x8 bf0 = *(const bf16x8*)(sb + T_BS + ((2 * t) * 16 + fr) * 272 + (k * 32 + fq * 8) * 2), bf1 = *(const bf16x8*)(sb + T_BS + ((2 * t + 1) * 16 + fr) * 272 + (k * 32 + fq * 8) * 2);
;                           s0 = mfma16(bf0, cf[k], s0); s1 = mfma16(bf1, cf[k], s1); }
;                       const f32x4 a0 = *(const f32x4*)(acP + (2 * t) * 16 + fq * 4), a1 = *(const f32x4*)(acP + (2 * t + 1) * 16 + fq * 4);
; #pragma unroll
;                       for (int j = 0; j < 4; ++j) { const int si0 = (2 * t) * 16 + fq * 4 + j, si1 = si0 + 16;
;                           const float e0 = s0[j] * __expf(fminf(acl_fr - a0[j], 0.f)), e1 = s1[j] * __expf(fminf(acl_fr - a1[j], 0.f));
;                           m[j] = (si0 <= lrow) ? e0 : 0.f; m[4 + j] = (si1 <= lrow) ? e1 : 0.f; } }
;                     v4u mp; mp.x = cvt_pk_bf16(m[0], m[1]); mp.y = cvt_pk_bf16(m[2], m[3]); mp.z = cvt_pk_bf16(m[4], m[5]); mp.w = cvt_pk_bf16(m[6], m[7]);
;                     asm volatile("s_waitcnt lgkmcnt(0)" : "+v"(xb0), "+v"(xb1) :: "memory");
;                     yo = mfma16(__builtin_bit_cast(bf16x8, mp), mk8(xb0, xb1), yo);
.Lssd_loop3:
	ds_read_b128 v[28:31], v219 offset:12288
	ds_read_b128 v[48:51], v227
	ds_read_b128 v[32:35], v220 offset:12288
	ds_read_b128 v[52:55], v228
	ds_read_b128 v[40:43], v221 offset:12288
	ds_read_b128 v[56:59], v229
	ds_read_b128 v[44:47], v222 offset:12288
	ds_read_b128 v[60:63], v230
	ds_read_b32 v194, v231 offset:192
	ds_read_b128 v[64:67], v219 offset:16384
	ds_read_b128 v[68:71], v220 offset:16384
	ds_read_b128 v[72:75], v221 offset:16384
	ds_read_b128 v[76:79], v222 offset:16384
	ds_read_b128 v[80:83], v219 offset:20480
	ds_read_b128 v[84:87], v220 offset:20480
	global_load_dwordx4 v[140:143], v204, s[40:41] offset:2048
	s_waitcnt lgkmcnt(11)
	ds_read_b128 v[88:91], v221 offset:20480
	ds_read_b128 v[92:95], v222 offset:20480
	ds_read_b128 v[96:99], v232
	ds_read_b128 v[100:103], v232 offset:64
	s_waitcnt lgkmcnt(11)
	ds_read_b64 v[124:125], v235 offset:46464
	ds_read_b64 v[126:127], v235 offset:51072
	global_load_dwordx4 v[144:147], v205, s[40:41] offset:2048
	v_mfma_f32_16x16x32_bf16 v[24:27], v[48:51], v[28:31], 0
	v_mfma_f32_16x16x32_bf16 v[188:191], v[52:55], v[32:35], 0
	v_mfma_f32_16x16x32_bf16 v[24:27], v[56:59], v[40:43], v[24:27]
	v_mfma_f32_16x16x32_bf16 v[188:191], v[60:63], v[44:47], v[188:191]
	ds_read_b64_tr_b16 v[56:57], v233 offset:32768
	ds_read_b64_tr_b16 v[58:59], v233 offset:34048
	s_waitcnt lgkmcnt(13)
	v_mfma_f32_16x16x32_bf16 v[48:51], v[64:67], v[28:31], 0
	global_load_dwordx4 v[132:135], v204, s[40:41]
	s_waitcnt lgkmcnt(9)
	v_mfma_f32_16x16x32_bf16 v[52:55], v[80:83], v[28:31], 0
	v_mfma_f32_16x16x32_bf16 v[48:51], v[68:71], v[32:35], v[48:51]
	s_waitcnt lgkmcnt(8)
	v_mfma_f32_16x16x32_bf16 v[52:55], v[84:87], v[32:35], v[52:55]
	v_mfma_f32_16x16x32_bf16 v[48:51], v[72:75], v[40:43], v[48:51]
	s_waitcnt lgkmcnt(7)
	v_mfma_f32_16x16x32_bf16 v[52:55], v[88:91], v[40:43], v[52:55]
	v_mfma_f32_16x16x32_bf16 v[48:51], v[76:79], v[44:47], v[48:51]
	s_waitcnt lgkmcnt(6)
	v_mfma_f32_16x16x32_bf16 v[52:55], v[92:95], v[44:47], v[52:55]
	global_load_dwordx4 v[136:139], v205, s[40:41]
	ds_read_b128 v[64:67], v219 offset:24576
	ds_read_b128 v[68:71], v220 offset:24576
	ds_read_b128 v[72:75], v221 offset:24576
	ds_read_b128 v[76:79], v222 offset:24576
	ds_read_b128 v[80:83], v219 offset:28672
	ds_read_b128 v[84:87], v220 offset:28672
	ds_read_b128 v[88:91], v221 offset:28672
	global_load_dwordx2 v[4:5], v206, s[40:41]
	ds_read_b128 v[92:95], v222 offset:28672
	ds_read_b64_tr_b16 v[60:61], v233 offset:35328
	s_waitcnt lgkmcnt(11)
	ds_read_b64_tr_b16 v[62:63], v233 offset:36608
	v_exp_f32_e32 v195, v194
	v_add_f32_e32 v24, v24, v188
	v_add_f32_e32 v25, v25, v189
	v_add_f32_e32 v26, v26, v190
	global_load_dwordx2 v[36:37], v207, s[42:43] nt
	v_add_f32_e32 v27, v27, v191
	v_mul_f32_e32 v24, v24, v195
	v_mul_f32_e32 v25, v25, v195
	v_mul_f32_e32 v26, v26, v195
	v_mul_f32_e32 v27, v27, v195
	v_lshlrev_b32_e32 v112, 16, v126
	v_and_b32_e32 v113, 0xffff0000, v126
	global_load_dword v6, v208, s[44:45]
	v_lshlrev_b32_e32 v114, 16, v127
	v_and_b32_e32 v115, 0xffff0000, v127
	v_mul_f32_e32 v120, 0xbfb8aa3b, v112
	v_mul_f32_e32 v121, 0xbfb8aa3b, v113
	v_mul_f32_e32 v122, 0xbfb8aa3b, v114
	v_mul_f32_e32 v123, 0xbfb8aa3b, v115
	global_load_dword v116, v208, s[46:47]
	v_exp_f32_e32 v120, v120
	v_exp_f32_e32 v121, v121
	v_exp_f32_e32 v122, v122
	v_exp_f32_e32 v123, v123
	v_add_f32_e32 v120, 1.0, v120
	v_add_f32_e32 v121, 1.0, v121
	v_add_f32_e32 v122, 1.0, v122
	global_load_dword v117, v209, s[46:47]
	v_add_f32_e32 v123, 1.0, v123
	v_rcp_f32_e32 v120, v120
	v_rcp_f32_e32 v121, v121
	v_rcp_f32_e32 v122, v122
	v_rcp_f32_e32 v123, v123
	v_mul_f32_e32 v112, v120, v112
	v_mul_f32_e32 v113, v121, v113
	s_add_u32 s66, s54, 3
	s_cmp_lt_u32 s66, s39
	s_cselect_b32 s74, 0xc0000, 0
	s_cselect_b32 s75, 0x280000, 0
	s_cselect_b32 s76, 0x4000, 0
	s_add_u32 s40, s40, s74
	s_addc_u32 s41, s41, 0
	s_add_u32 s42, s42, s75
	s_addc_u32 s43, s43, 0
	s_add_u32 s44, s44, s76
	s_addc_u32 s45, s45, 0
	s_add_u32 s46, s46, s76
	s_addc_u32 s47, s47, 0
	v_mul_f32_e32 v114, v122, v114
	v_mul_f32_e32 v115, v123, v115
	s_waitcnt vmcnt(10)
	v_lshlrev_b32_e32 v120, 16, v124
	v_and_b32_e32 v121, 0xffff0000, v124
	v_lshlrev_b32_e32 v122, 16, v125
	ds_write_b128 v213, v[156:159]
	v_and_b32_e32 v123, 0xffff0000, v125
	v_sub_f32_e32 v184, v194, v96
	ds_write_b128 v213, v[160:163] offset:8192
	v_sub_f32_e32 v185, v194, v97
	v_sub_f32_e32 v186, v194, v98
	ds_write_b128 v213, v[148:151] offset:16384
	v_sub_f32_e32 v187, v194, v99
	v_exp_f32_e32 v184, v184
	v_exp_f32_e32 v185, v185
	s_waitcnt lgkmcnt(11)
	ds_write_b128 v213, v[152:155] offset:24576
	v_exp_f32_e32 v186, v186
	v_exp_f32_e32 v187, v187
	v_sub_f32_e32 v200, v169, v168
	v_mul_f32_e32 v184, v48, v184
	v_mul_f32_e32 v185, v49, v185
	v_mul_f32_e32 v200, 0x3fb8aa3b, v200
	v_mul_f32_e32 v186, v50, v186
	v_mul_f32_e32 v187, v51, v187
	v_exp_f32_e32 v200, v200
	v_sub_f32_e32 v188, v194, v100
	v_sub_f32_e32 v189, v194, v101
	v_sub_f32_e32 v190, v194, v102
	v_lshlrev_b32_e32 v196, 16, v164
	v_sub_f32_e32 v191, v194, v103
	v_exp_f32_e32 v188, v188
	v_and_b32_e32 v197, 0xffff0000, v164
	v_exp_f32_e32 v189, v189
	v_exp_f32_e32 v190, v190
	v_lshlrev_b32_e32 v198, 16, v165
	v_exp_f32_e32 v191, v191
	v_mul_f32_e32 v188, v52, v188
	v_mul_f32_e32 v189, v53, v189
	v_and_b32_e32 v199, 0xffff0000, v165
	v_mul_f32_e32 v190, v54, v190
	v_mul_f32_e32 v191, v55, v191
	v_mul_f32_e32 v196, v196, v118
	v_cvt_pk_bf16_f32 v128, v184, v185
	v_cvt_pk_bf16_f32 v129, v186, v187
	v_mul_f32_e32 v197, v197, v118
	v_cvt_pk_bf16_f32 v130, v188, v189
	v_cvt_pk_bf16_f32 v131, v190, v191
	v_mul_f32_e32 v198, v198, v118
	s_nop 0
	v_mfma_f32_16x16x32_bf16 v[24:27], v[56:59], v[128:131], v[24:27]
	ds_read_b128 v[96:99], v232 offset:128
	ds_read_b128 v[100:103], v232 offset:192
	v_mul_f32_e32 v199, v199, v118
	v_mfma_f32_16x16x32_bf16 v[48:51], v[64:67], v[28:31], 0
	s_waitcnt lgkmcnt(11)
; __device__ __forceinline__ void phase_ssd(const Params& P, int seg, unsigned char* smem) {
;     ...
;             bf16x8 cf[4];
; #pragma unroll
;             for (int k = 0; k < 4; ++k) cf[k] = *(const bf16x8*)(sb + T_CS + (lt * 16 + fr) * 272 + (k * 32 + fq * 8) * 2);
;             f32x4 yo = {0.f, 0.f, 0.f, 0.f};
; #pragma unroll
;     ...
;             for (int t = 0; t < 2; ++t) {
;                 if (2 * t <= lt) {
;                     v2u xb0, xb1;
;                     { const unsigned a0 = lds0 + par * T_BUF + T_XD + (32 * t + 4 * fq + tq) * 80 + (pt * 16 + 4 * tp) * 2, a1 = a0 + 16 * 80; TR_ISSUE(xb0, a0); TR_ISSUE(xb1, a1); }
;                     float m[8];
;                     { f32x4 s0 = {0.f, 0.f, 0.f, 0.f}, s1 = {0.f, 0.f, 0.f, 0.f};
; #pragma unroll
;                       for (int k = 0; k < 4; ++k) { const bf16x8 bf0 = *(const bf16x8*)(sb + T_BS + ((2 * t) * 16 + fr) * 272 + (k * 32 + fq * 8) * 2), bf1 = *(const bf16x8*)(sb + T_BS + ((2 * t + 1) * 16 + fr) * 272 + (k * 32 + fq * 8) * 2);
;                           s0 = mfma16(bf0, cf[k], s0); s1 = mfma16(bf1, cf[k], s1); }
;                       const f32x4 a0 = *(const f32x4*)(acP + (2 * t) * 16 + fq * 4), a1 = *(const f32x4*)(acP + (2 * t + 1) * 16 + fq * 4);
; #pragma unroll
;                       for (int j = 0; j < 4; ++j) { const int si0 = (2 * t) * 16 + fq * 4 + j, si1 = si0 + 16;
;                           const float e0 = s0[j] * __expf(fminf(acl_fr - a0[j], 0.f)), e1 = s1[j] * __expf(fminf(acl_fr - a1[j], 0.f));
;                           m[j] = (si0 <= lrow) ? e0 : 0.f; m[4 + j] = (si1 <= lrow) ? e1 : 0.f; } }
;                     v4u mp; mp.x = cvt_pk_bf16(m[0], m[1]); mp.y = cvt_pk_bf16(m[2], m[3]); mp.z = cvt_pk_bf16(m[4], m[5]); mp.w = cvt_pk_bf16(m[6], m[7]);
;                     asm volatile("s_waitcnt lgkmcnt(0)" : "+v"(xb0), "+v"(xb1) :: "memory");
;                     yo = mfma16(__builtin_bit_cast(bf16x8, mp), mk8(xb0, xb1), yo);
;                 }
;             }
; #pragma unroll
;             for (int j = 0; j < 4; ++j) { const int l = lt * 16 + fq * 4 + j, p = pt * 16 + fr; const float xv = bf2f(*(const bf16*)(sb + T_XS + l * 64 + p * 2)), zv = bf2f(*(const bf16*)(sb + T_ZS + l * 64 + p * 2));
;                 ypre[(size_t)(row0 + l) * DINNER + h * 64 + ph * 32 + p] = f2bfh((yo[j] + Dh * xv) * siluf_(zv)); }
	v_mfma_f32_16x16x32_bf16 v[52:55], v[80:83], v[28:31], 0
	v_cvt_pk_bf16_f32 v202, v196, v197
	v_mfma_f32_16x16x32_bf16 v[48:51], v[68:71], v[32:35], v[48:51]
	s_waitcnt lgkmcnt(10)
	v_mfma_f32_16x16x32_bf16 v[52:55], v[84:87], v[32:35], v[52:55]
	v_cvt_pk_bf16_f32 v203, v198, v199
	v_mfma_f32_16x16x32_bf16 v[48:51], v[72:75], v[40:43], v[48:51]
	s_waitcnt lgkmcnt(9)
	v_mfma_f32_16x16x32_bf16 v[52:55], v[88:91], v[40:43], v[52:55]
	v_mfma_f32_16x16x32_bf16 v[48:51], v[76:79], v[44:47], v[48:51]
	ds_write_b64 v215, v[202:203] offset:32768
	s_waitcnt lgkmcnt(9)
	v_mfma_f32_16x16x32_bf16 v[52:55], v[92:95], v[44:47], v[52:55]
	s_waitcnt lgkmcnt(2)
	v_sub_f32_e32 v184, v194, v96
	v_mul_f32_e32 v196, v196, v200
	v_sub_f32_e32 v185, v194, v97
	v_sub_f32_e32 v186, v194, v98
	v_mul_f32_e32 v197, v197, v200
	v_sub_f32_e32 v187, v194, v99
	v_exp_f32_e32 v184, v184
	v_mul_f32_e32 v198, v198, v200
	v_exp_f32_e32 v185, v185
	v_exp_f32_e32 v186, v186
	v_exp_f32_e32 v187, v187
	v_mul_f32_e32 v199, v199, v200
	v_mul_f32_e32 v184, v48, v184
	v_mul_f32_e32 v185, v49, v185
	v_cvt_pk_bf16_f32 v192, v196, v197
	v_mul_f32_e32 v186, v50, v186
	v_mul_f32_e32 v187, v51, v187
	v_cvt_pk_bf16_f32 v193, v198, v199
	s_waitcnt lgkmcnt(1)
	v_sub_f32_e32 v188, v194, v100
	v_sub_f32_e32 v189, v194, v101
	v_sub_f32_e32 v190, v194, v102
	ds_write_b64 v215, v[192:193] offset:37888
	v_sub_f32_e32 v191, v194, v103
	v_exp_f32_e32 v188, v188
	ds_write_b64 v217, v[164:165] offset:43008
	v_exp_f32_e32 v189, v189
	v_exp_f32_e32 v190, v190
	ds_write_b64 v217, v[166:167] offset:47616
	v_exp_f32_e32 v191, v191
	v_mul_f32_e32 v188, v52, v188
	v_mul_f32_e32 v201, 0x3fb8aa3b, v168
	v_mul_f32_e32 v189, v53, v189
	v_mul_f32_e32 v190, v54, v190
	v_mul_f32_e32 v191, v55, v191
	ds_write_b32 v218, v201 offset:256
	v_cndmask_b32_e64 v188, 0, v188, s[14:15]
	v_cndmask_b32_e64 v189, 0, v189, s[16:17]
	v_mul_f32_e32 v174, 0x3fb8aa3b, v169
	v_cndmask_b32_e64 v190, 0, v190, s[22:23]
	v_cndmask_b32_e64 v191, 0, v191, s[34:35]
	v_exp_f32_e32 v174, v174
	v_cvt_pk_bf16_f32 v128, v184, v185
	v_cvt_pk_bf16_f32 v129, v186, v187
	v_cvt_pk_bf16_f32 v130, v188, v189
	v_cvt_pk_bf16_f32 v131, v190, v191
	s_nop 1
	v_mfma_f32_16x16x32_bf16 v[24:27], v[60:63], v[128:131], v[24:27]
	s_mul_i32 s65, s56, 0x2000
	s_add_u32 s65, s65, 0x304f1000
	s_add_u32 s48, s0, s65
	s_addc_u32 s49, s1, 0
	s_nop 3
	v_fma_f32 v184, s61, v120, v24
	v_fma_f32 v185, s61, v121, v25
	v_fma_f32 v186, s61, v122, v26
	v_fma_f32 v187, s61, v123, v27
	v_mul_f32_e32 v184, v184, v112
	v_mul_f32_e32 v185, v185, v113
	v_mul_f32_e32 v186, v186, v114
	v_mul_f32_e32 v187, v187, v115
	v_cvt_pk_bf16_f32 v170, v184, v185
	v_cvt_pk_bf16_f32 v171, v186, v187
	global_store_dwordx2 v210, v[170:171], s[48:49]
	s_add_u32 s65, s54, 1
	s_sub_u32 s65, s65, s60
	s_lshl_b32 s65, s65, 6
	s_add_u32 s56, s65, s20
	s_waitcnt lgkmcnt(0)
	s_barrier
	s_add_u32 s54, s54, 1
	s_cmp_ge_u32 s54, s39
	s_cbranch_scc1 .Lssd_done
	ds_read_b128 v[28:31], v223 offset:12288
	ds_read_b128 v[48:51], v227 offset:8192
	ds_read_b128 v[32:35], v224 offset:12288
	ds_read_b128 v[52:55], v228 offset:8192
	ds_read_b128 v[40:43], v225 offset:12288
	ds_read_b128 v[56:59], v229 offset:8192
	ds_read_b128 v[44:47], v226 offset:12288
	ds_read_b128 v[60:63], v230 offset:8192
	ds_read_b32 v194, v231 offset:448
	ds_read_b128 v[64:67], v223 offset:16384
	ds_read_b128 v[68:71], v224 offset:16384
	ds_read_b128 v[72:75], v225 offset:16384
	ds_read_b128 v[76:79], v226 offset:16384
	ds_read_b128 v[80:83], v223 offset:20480
	ds_read_b128 v[84:87], v224 offset:20480
	global_load_dwordx4 v[156:159], v204, s[40:41] offset:2048
	s_waitcnt lgkmcnt(11)
	ds_read_b128 v[88:91], v225 offset:20480
	ds_read_b128 v[92:95], v226 offset:20480
	ds_read_b128 v[96:99], v232 offset:256
	ds_read_b128 v[100:103], v232 offset:320
	s_waitcnt lgkmcnt(11)
	ds_read_b64 v[124:125], v236 offset:46464
	ds_read_b64 v[126:127], v236 offset:51072
	global_load_dwordx4 v[160:163], v205, s[40:41] offset:2048
	v_mfma_f32_16x16x32_bf16 v[24:27], v[48:51], v[28:31], 0
	v_mfma_f32_16x16x32_bf16 v[188:191], v[52:55], v[32:35], 0
	v_mfma_f32_16x16x32_bf16 v[24:27], v[56:59], v[40:43], v[24:27]
	v_mfma_f32_16x16x32_bf16 v[188:191], v[60:63], v[44:47], v[188:191]
	ds_read_b64_tr_b16 v[56:57], v234 offset:32768
	ds_read_b64_tr_b16 v[58:59], v234 offset:34048
	s_waitcnt lgkmcnt(13)
	v_mfma_f32_16x16x32_bf16 v[48:51], v[64:67], v[28:31], 0
	global_load_dwordx4 v[148:151], v204, s[40:41]
	s_waitcnt lgkmcnt(9)
	v_mfma_f32_16x16x32_bf16 v[52:55], v[80:83], v[28:31], 0
	v_mfma_f32_16x16x32_bf16 v[48:51], v[68:71], v[32:35], v[48:51]
	s_waitcnt lgkmcnt(8)
	v_mfma_f32_16x16x32_bf16 v[52:55], v[84:87], v[32:35], v[52:55]
	v_mfma_f32_16x16x32_bf16 v[48:51], v[72:75], v[40:43], v[48:51]
	s_waitcnt lgkmcnt(7)
	v_mfma_f32_16x16x32_bf16 v[52:55], v[88:91], v[40:43], v[52:55]
	v_mfma_f32_16x16x32_bf16 v[48:51], v[76:79], v[44:47], v[48:51]
	s_waitcnt lgkmcnt(6)
	v_mfma_f32_16x16x32_bf16 v[52:55], v[92:95], v[44:47], v[52:55]
	global_load_dwordx4 v[152:155], v205, s[40:41]
	ds_read_b128 v[64:67], v223 offset:24576
	ds_read_b128 v[68:71], v224 offset:24576
	ds_read_b128 v[72:75], v225 offset:24576
	ds_read_b128 v[76:79], v226 offset:24576
	ds_read_b128 v[80:83], v223 offset:28672
	ds_read_b128 v[84:87], v224 offset:28672
	ds_read_b128 v[88:91], v225 offset:28672
	global_load_dwordx2 v[164:165], v206, s[40:41]
	ds_read_b128 v[92:95], v226 offset:28672
	ds_read_b64_tr_b16 v[60:61], v234 offset:35328
	s_waitcnt lgkmcnt(11)
; __device__ __forceinline__ unsigned cvt_pk_bf16(float lo, float hi) { unsigned r; asm volatile("v_cvt_pk_bf16_f32 %0, %1, %2" : "=v"(r) : "v"(lo), "v"(hi)); return r; }
; __device__ __forceinline__ void phase_ssd(const Params& P, int seg, unsigned char* smem) {
;     ...
;             { const float e2 = __expf(R.alast - R.acl);
; #pragma unroll
;               for (int i = 0; i < 2; ++i) { const int q = tid + 512 * i, l = q >> 4, c8 = q & 15; *(v4u*)(sb + T_CS + l * 272 + c8 * 16) = R.Cr[i]; *(v4u*)(sb + T_BS + l * 272 + c8 * 16) = R.Br[i]; }
;               const int l = tid >> 3, p4 = (tid & 7) * 4;
;               const float x0 = bflo(R.Xr.x) * R.dtl, x1 = bfhi(R.Xr.x) * R.dtl, x2 = bflo(R.Xr.y) * R.dtl, x3 = bfhi(R.Xr.y) * R.dtl;
;               v2u d; d.x = cvt_pk_bf16(x0, x1); d.y = cvt_pk_bf16(x2, x3); *(v2u*)(sb + T_XD + l * 80 + p4 * 2) = d;
;               v2u e; e.x = cvt_pk_bf16(x0 * e2, x1 * e2); e.y = cvt_pk_bf16(x2 * e2, x3 * e2); *(v2u*)(sb + T_XE + l * 80 + p4 * 2) = e;
;               *(v2u*)(sb + T_XS + l * 64 + p4 * 2) = R.Xr; *(v2u*)(sb + T_ZS + l * 64 + p4 * 2) = R.Zr;
;               if (w == 0) acP[lane] = R.aclane; }
;             BAR_LDS();
;             if (ci + 2 < nchunks) load_chunk(ci + 2, R);
;             bf16x8 cf[4];
; #pragma unroll
;             for (int k = 0; k < 4; ++k) cf[k] = *(const bf16x8*)(sb + T_CS + (lt * 16 + fr) * 272 + (k * 32 + fq * 8) * 2);
;             f32x4 yo = {0.f, 0.f, 0.f, 0.f};
; #pragma unroll
;             for (int k = 0; k < 4; ++k) { const bf16x8 bb = *(const bf16x8*)((const unsigned char*)StR + (pt * 16 + fr) * 272 + (k * 32 + fq * 8) * 2); yo = mfma16(cf[k], bb, yo); }
; { const f32x4 a4 = *(const f32x4*)(acP + lt * 16 + fq * 4);
; #pragma unroll
;               for (int j = 0; j < 4; ++j) yo[j] *= __expf(a4[j]); }
;             const float acl_fr = acP[lt * 16 + fr]; const int lrow = lt * 16 + fr;
; #pragma unroll
;             for (int t = 0; t < 2; ++t) {
;                 if (2 * t <= lt) {
;                     v2u xb0, xb1;
;                     { const unsigned a0 = lds0 + par * T_BUF + T_XD + (32 * t + 4 * fq + tq) * 80 + (pt * 16 + 4 * tp) * 2, a1 = a0 + 16 * 80; TR_ISSUE(xb0, a0); TR_ISSUE(xb1, a1); }
;                     float m[8];
;                     { f32x4 s0 = {0.f, 0.f, 0.f, 0.f}, s1 = {0.f, 0.f, 0.f, 0.f};
; #pragma unroll
	ds_read_b64_tr_b16 v[62:63], v234 offset:36608
	v_exp_f32_e32 v195, v194
	v_add_f32_e32 v24, v24, v188
	v_add_f32_e32 v25, v25, v189
	v_add_f32_e32 v26, v26, v190
	global_load_dwordx2 v[166:167], v207, s[42:43] nt
	v_add_f32_e32 v27, v27, v191
	v_mul_f32_e32 v24, v24, v195
	v_mul_f32_e32 v25, v25, v195
	v_mul_f32_e32 v26, v26, v195
	v_mul_f32_e32 v27, v27, v195
	v_lshlrev_b32_e32 v112, 16, v126
	v_and_b32_e32 v113, 0xffff0000, v126
	global_load_dword v118, v208, s[44:45]
	v_lshlrev_b32_e32 v114, 16, v127
	v_and_b32_e32 v115, 0xffff0000, v127
	v_mul_f32_e32 v120, 0xbfb8aa3b, v112
	v_mul_f32_e32 v121, 0xbfb8aa3b, v113
	v_mul_f32_e32 v122, 0xbfb8aa3b, v114
	v_mul_f32_e32 v123, 0xbfb8aa3b, v115
	global_load_dword v168, v208, s[46:47]
	v_exp_f32_e32 v120, v120
	v_exp_f32_e32 v121, v121
	v_exp_f32_e32 v122, v122
	v_exp_f32_e32 v123, v123
	v_add_f32_e32 v120, 1.0, v120
	v_add_f32_e32 v121, 1.0, v121
	v_add_f32_e32 v122, 1.0, v122
	global_load_dword v169, v209, s[46:47]
	v_add_f32_e32 v123, 1.0, v123
	v_rcp_f32_e32 v120, v120
	v_rcp_f32_e32 v121, v121
	v_rcp_f32_e32 v122, v122
	v_rcp_f32_e32 v123, v123
	v_mul_f32_e32 v112, v120, v112
	v_mul_f32_e32 v113, v121, v113
	s_add_u32 s66, s54, 3
	s_cmp_lt_u32 s66, s39
	s_cselect_b32 s74, 0xc0000, 0
	s_cselect_b32 s75, 0x280000, 0
	s_cselect_b32 s76, 0x4000, 0
	s_add_u32 s40, s40, s74
	s_addc_u32 s41, s41, 0
	s_add_u32 s42, s42, s75
	s_addc_u32 s43, s43, 0
	s_add_u32 s44, s44, s76
	s_addc_u32 s45, s45, 0
	s_add_u32 s46, s46, s76
	s_addc_u32 s47, s47, 0
	v_mul_f32_e32 v114, v122, v114
	v_mul_f32_e32 v115, v123, v115
	s_waitcnt vmcnt(10)
	v_lshlrev_b32_e32 v120, 16, v124
	v_and_b32_e32 v121, 0xffff0000, v124
	v_lshlrev_b32_e32 v122, 16, v125
	ds_write_b128 v212, v[140:143]
	v_and_b32_e32 v123, 0xffff0000, v125
	v_sub_f32_e32 v184, v194, v96
	ds_write_b128 v212, v[144:147] offset:8192
	v_sub_f32_e32 v185, v194, v97
	v_sub_f32_e32 v186, v194, v98
	ds_write_b128 v212, v[132:135] offset:16384
	v_sub_f32_e32 v187, v194, v99
	v_exp_f32_e32 v184, v184
	v_exp_f32_e32 v185, v185
	s_waitcnt lgkmcnt(11)
	ds_write_b128 v212, v[136:139] offset:24576
	v_exp_f32_e32 v186, v186
	v_exp_f32_e32 v187, v187
	v_sub_f32_e32 v200, v117, v116
	v_mul_f32_e32 v184, v48, v184
	v_mul_f32_e32 v185, v49, v185
	v_mul_f32_e32 v200, 0x3fb8aa3b, v200
	v_mul_f32_e32 v186, v50, v186
	v_mul_f32_e32 v187, v51, v187
	v_exp_f32_e32 v200, v200
	v_sub_f32_e32 v188, v194, v100
	v_sub_f32_e32 v189, v194, v101
	v_sub_f32_e32 v190, v194, v102
	v_lshlrev_b32_e32 v196, 16, v4
	v_sub_f32_e32 v191, v194, v103
	v_exp_f32_e32 v188, v188
	v_and_b32_e32 v197, 0xffff0000, v4
	v_exp_f32_e32 v189, v189
	v_exp_f32_e32 v190, v190
	v_lshlrev_b32_e32 v198, 16, v5
	v_exp_f32_e32 v191, v191
	v_mul_f32_e32 v188, v52, v188
	v_mul_f32_e32 v189, v53, v189
	v_and_b32_e32 v199, 0xffff0000, v5
	v_mul_f32_e32 v190, v54, v190
	v_mul_f32_e32 v191, v55, v191
	v_mul_f32_e32 v196, v196, v6
	v_cvt_pk_bf16_f32 v128, v184, v185
	v_cvt_pk_bf16_f32 v129, v186, v187
	v_mul_f32_e32 v197, v197, v6
	v_cvt_pk_bf16_f32 v130, v188, v189
	v_cvt_pk_bf16_f32 v131, v190, v191
	v_mul_f32_e32 v198, v198, v6
	s_nop 0
	v_mfma_f32_16x16x32_bf16 v[24:27], v[56:59], v[128:131], v[24:27]
	ds_read_b128 v[96:99], v232 offset:384
	ds_read_b128 v[100:103], v232 offset:448
	v_mul_f32_e32 v199, v199, v6
	v_mfma_f32_16x16x32_bf16 v[48:51], v[64:67], v[28:31], 0
	s_waitcnt lgkmcnt(11)
	v_mfma_f32_16x16x32_bf16 v[52:55], v[80:83], v[28:31], 0
	v_cvt_pk_bf16_f32 v202, v196, v197
	v_mfma_f32_16x16x32_bf16 v[48:51], v[68:71], v[32:35], v[48:51]
	s_waitcnt lgkmcnt(10)
	v_mfma_f32_16x16x32_bf16 v[52:55], v[84:87], v[32:35], v[52:55]
	v_cvt_pk_bf16_f32 v203, v198, v199
	v_mfma_f32_16x16x32_bf16 v[48:51], v[72:75], v[40:43], v[48:51]
	s_waitcnt lgkmcnt(9)
	v_mfma_f32_16x16x32_bf16 v[52:55], v[88:91], v[40:43], v[52:55]
	v_mfma_f32_16x16x32_bf16 v[48:51], v[76:79], v[44:47], v[48:51]
	ds_write_b64 v214, v[202:203] offset:32768
	s_waitcnt lgkmcnt(9)
	v_mfma_f32_16x16x32_bf16 v[52:55], v[92:95], v[44:47], v[52:55]
	s_waitcnt lgkmcnt(2)
	v_sub_f32_e32 v184, v194, v96
	v_mul_f32_e32 v196, v196, v200
	v_sub_f32_e32 v185, v194, v97
	v_sub_f32_e32 v186, v194, v98
	v_mul_f32_e32 v197, v197, v200
	v_sub_f32_e32 v187, v194, v99
	v_exp_f32_e32 v184, v184
	v_mul_f32_e32 v198, v198, v200
	v_exp_f32_e32 v185, v185
	v_exp_f32_e32 v186, v186
	v_exp_f32_e32 v187, v187
	v_mul_f32_e32 v199, v199, v200
	v_mul_f32_e32 v184, v48, v184
	v_mul_f32_e32 v185, v49, v185
	v_cvt_pk_bf16_f32 v192, v196, v197
	v_mul_f32_e32 v186, v50, v186
	v_mul_f32_e32 v187, v51, v187
	v_cvt_pk_bf16_f32 v193, v198, v199
	s_waitcnt lgkmcnt(1)
	v_sub_f32_e32 v188, v194, v100
	v_sub_f32_e32 v189, v194, v101
	v_sub_f32_e32 v190, v194, v102
	ds_write_b64 v214, v[192:193] offset:37888
	v_sub_f32_e32 v191, v194, v103
	v_exp_f32_e32 v188, v188
	ds_write_b64 v216, v[4:5] offset:43008
	v_exp_f32_e32 v189, v189
	v_exp_f32_e32 v190, v190
	ds_write_b64 v216, v[36:37] offset:47616
	v_exp_f32_e32 v191, v191
	v_mul_f32_e32 v188, v52, v188
	v_mul_f32_e32 v201, 0x3fb8aa3b, v116
	v_mul_f32_e32 v189, v53, v189
	v_mul_f32_e32 v190, v54, v190
	v_mul_f32_e32 v191, v55, v191
	ds_write_b32 v218, v201
	v_cndmask_b32_e64 v188, 0, v188, s[14:15]
	v_cndmask_b32_e64 v189, 0, v189, s[16:17]
	v_mul_f32_e32 v174, 0x3fb8aa3b, v117
	v_cndmask_b32_e64 v190, 0, v190, s[22:23]
	v_cndmask_b32_e64 v191, 0, v191, s[34:35]
	v_exp_f32_e32 v174, v174
	v_cvt_pk_bf16_f32 v128, v184, v185
	v_cvt_pk_bf16_f32 v129, v186, v187
	v_cvt_pk_bf16_f32 v130, v188, v189
	v_cvt_pk_bf16_f32 v131, v190, v191
	s_nop 1
	v_mfma_f32_16x16x32_bf16 v[24:27], v[60:63], v[128:131], v[24:27]
	s_mul_i32 s65, s56, 0x2000
	s_add_u32 s65, s65, 0x304f1000
	s_add_u32 s48, s0, s65
	s_addc_u32 s49, s1, 0
	s_nop 3
	v_fma_f32 v184, s61, v120, v24
	v_fma_f32 v185, s61, v121, v25
	v_fma_f32 v186, s61, v122, v26
	v_fma_f32 v187, s61, v123, v27
	v_mul_f32_e32 v184, v184, v112
	v_mul_f32_e32 v185, v185, v113
	v_mul_f32_e32 v186, v186, v114
	v_mul_f32_e32 v187, v187, v115
	v_cvt_pk_bf16_f32 v170, v184, v185
	v_cvt_pk_bf16_f32 v171, v186, v187
	global_store_dwordx2 v210, v[170:171], s[48:49]
	s_add_u32 s65, s54, 1
	s_sub_u32 s65, s65, s60
	s_lshl_b32 s65, s65, 6
	s_add_u32 s56, s65, s20
	s_waitcnt lgkmcnt(0)
	s_barrier
	s_add_u32 s54, s54, 1
	s_cmp_lt_u32 s54, s39
	s_cbranch_scc1 .Lssd_loop3
